# stack: v042 + LRU re-tile + batch-3 x prefetch in stats residual epilogues + counted waits in out-proj L0 epilogue
# speedup vs baseline: 1.0073x; 1.0073x over previous
; #define EPIRES_LOAD(q_, buf_) do { const int bj_ = (q_) >> 1, ai_ = (q_) & 1; \
;             _Pragma("unroll") for (int m = 0; m < 4; ++m) { const float* xp = Xin + (size_t)(row0 + ai_ * HALF + m * 16) * D + col0 + bj_ * HALF; xa[buf_][m] = *(const f32x4*)xp; xb[buf_][m] = *(const f32x4*)(xp + 4); } } while (0)
;     __device__ __forceinline__ void operator()(const f32x4 (&acc)[2][2][4][2], const Unit& u, int wr, int wc, int fr, int fq) const {
;         typedef float f32x2_t __attribute__((ext_vector_type(2)));
;         const int row0 = u.pm * BM + wr * 64 + fr, col0 = u.pn * BM + wc * 32 + 8 * fq;
;         const float* gp = gate + (size_t)((u.pm * BM) >> 11) * 6144 + col0;
;         f32x2_t st[2][4];
; #pragma unroll
;         for (int ai = 0; ai < 2; ++ai)
; #pragma unroll
;             for (int m = 0; m < 4; ++m) st[ai][m] = stats ? *(const f32x2_t*)(stats + 2 * (row0 + ai * HALF + m * 16)) : (f32x2_t){0.f, 1.f};
;         f32x4 xa[2][4], xb[2][4];
;     ...
;         EPIRES_LOAD(0, 0);
; #pragma unroll
;         for (int q = 0; q < 4; ++q) { const int bj = q >> 1, ai = q & 1, co = col0 + bj * HALF, cb = q & 1;
;             if (q + 1 < 4) EPIRES_LOAD(q + 1, cb ^ 1);
;             const f32x4 g0 = *(const f32x4*)(gp + bj * HALF), g1 = *(const f32x4*)(gp + bj * HALF + 4);
;             f32x4 w0 = {1.f, 1.f, 1.f, 1.f}, w1 = w0, b0 = {0.f, 0.f, 0.f, 0.f}, b1 = b0;
;             if (stats) { w0 = *(const f32x4*)(lw + co); w1 = *(const f32x4*)(lw + co + 4); b0 = *(const f32x4*)(lb + co); b1 = *(const f32x4*)(lb + co + 4); }
; #pragma unroll
;             for (int m = 0; m < 4; ++m) { float* op = Xout + (size_t)(row0 + ai * HALF + m * 16) * D + co;
;                 f32x4 x0 = xa[cb][m], x1 = xb[cb][m];
;                 if (stats) { x0 = (x0 - st[ai][m].x) * st[ai][m].y * w0 + b0; x1 = (x1 - st[ai][m].x) * st[ai][m].y * w1 + b1; }
;                 *(f32x4*)op = x0 * ALPHA + g0 * acc[ai][bj][m][0]; *(f32x4*)(op + 4) = x1 * ALPHA + g1 * acc[ai][bj][m][1]; } }
.LBB0_693:
	v_lshl_add_u32 v140, s62, 8, v182
	v_lshl_add_u32 v142, s63, 8, v184
	v_ashrrev_i32_e32 v143, 31, v142
	v_lshlrev_b32_e32 v144, 1, v140
	v_ashrrev_i32_e32 v145, 31, v144
	v_lshlrev_b64 v[168:169], 2, v[142:143]
	v_ashrrev_i32_e32 v141, 31, v140
	v_lshl_add_u64 v[152:153], v[144:145], 2, s[20:21]
	v_lshl_add_u64 v[176:177], s[18:19], 0, v[168:169]
	v_lshlrev_b64 v[178:179], 12, v[140:141]
	s_ashr_i32 s42, s62, 3
	flat_load_dwordx2 v[158:159], v[152:153]
	v_lshl_add_u64 v[164:165], v[176:177], 0, v[178:179]
	s_mul_hi_i32 s43, s42, 0x6000
	s_mulk_i32 s42, 0x6000
	flat_load_dwordx4 v[188:191], v[164:165]
	flat_load_dwordx4 v[192:195], v[164:165] offset:16
	s_add_u32 s42, s52, s42
	s_addc_u32 s43, s53, s43
	v_lshl_add_u64 v[148:149], s[10:11], 0, v[168:169]
	v_lshl_add_u64 v[150:151], s[42:43], 0, v[168:169]
	v_lshl_add_u64 v[146:147], s[8:9], 0, v[168:169]
	flat_load_dwordx4 v[196:199], v[148:149]
	flat_load_dwordx4 v[200:203], v[146:147]
	flat_load_dwordx4 v[204:207], v[146:147] offset:16
	flat_load_dwordx4 v[208:211], v[148:149] offset:16
	flat_load_dwordx4 v[212:215], v[150:151]
	flat_load_dwordx4 v[216:219], v[150:151] offset:16
	v_or_b32_e32 v142, 16, v140
	v_ashrrev_i32_e32 v143, 31, v142
	v_lshlrev_b64 v[250:251], 12, v[142:143]
	flat_load_dwordx2 v[162:163], v[152:153] offset:128
	v_lshl_add_u64 v[170:171], v[176:177], 0, v[250:251]
	flat_load_dwordx4 v[220:223], v[170:171]
	flat_load_dwordx4 v[224:227], v[170:171] offset:16
	v_or_b32_e32 v142, 32, v140
	v_ashrrev_i32_e32 v143, 31, v142
	v_lshlrev_b64 v[252:253], 12, v[142:143]
	v_lshl_add_u64 v[172:173], v[176:177], 0, v[252:253]
	flat_load_dwordx2 v[160:161], v[152:153] offset:256
	flat_load_dwordx4 v[228:231], v[172:173]
	flat_load_dwordx4 v[232:235], v[172:173] offset:16
	flat_load_dwordx2 v[156:157], v[152:153] offset:384
	v_or_b32_e32 v140, 48, v140
	v_add_u32_e32 v154, 0x100, v144
	v_add_u32_e32 v166, 0x120, v144
	v_add_u32_e32 v174, 0x140, v144
	v_add_u32_e32 v144, 0x160, v144
	v_ashrrev_i32_e32 v141, 31, v140
	v_ashrrev_i32_e32 v155, 31, v154
	v_ashrrev_i32_e32 v167, 31, v166
	v_ashrrev_i32_e32 v175, 31, v174
	v_ashrrev_i32_e32 v145, 31, v144
	v_lshlrev_b64 v[248:249], 12, v[140:141]
	v_lshl_add_u64 v[180:181], v[178:179], 0, s[26:27]
	v_lshl_add_u64 v[140:141], s[18:19], 0, v[178:179]
	v_lshl_add_u64 v[142:143], v[154:155], 2, s[20:21]
	v_lshl_add_u64 v[236:237], v[166:167], 2, s[20:21]
	v_lshl_add_u64 v[238:239], v[174:175], 2, s[20:21]
	v_lshl_add_u64 v[240:241], v[144:145], 2, s[20:21]
	v_lshl_add_u64 v[174:175], v[176:177], 0, v[248:249]
	v_lshl_add_u64 v[154:155], v[176:177], 0, v[180:181]
	v_lshl_add_u64 v[166:167], v[140:141], 0, v[168:169]
	flat_load_dwordx2 v[152:153], v[142:143]
	flat_load_dwordx2 v[144:145], v[236:237]
	s_nop 0
	flat_load_dwordx2 v[142:143], v[238:239]
	flat_load_dwordx2 v[140:141], v[240:241]
	s_nop 0
	flat_load_dwordx4 v[236:239], v[174:175]
	flat_load_dwordx4 v[240:243], v[174:175] offset:16
	flat_load_dwordx4 v[244:247], v[154:155]
	s_and_b64 vcc, exec, s[4:5]
	s_mov_b64 s[4:5], -1
	s_waitcnt vmcnt(0) lgkmcnt(0)
	v_sub_f32_e32 v191, v191, v158
	v_sub_f32_e32 v190, v190, v158
	v_sub_f32_e32 v189, v189, v158
	v_sub_f32_e32 v188, v188, v158
	v_pk_mul_f32 v[188:189], v[158:159], v[188:189] op_sel:[1,0]
	v_pk_mul_f32 v[190:191], v[158:159], v[190:191] op_sel:[1,0]
	v_sub_f32_e32 v195, v195, v158
	v_sub_f32_e32 v194, v194, v158
	v_sub_f32_e32 v193, v193, v158
	v_sub_f32_e32 v192, v192, v158
	v_pk_fma_f32 v[190:191], v[190:191], v[202:203], v[198:199]
	v_pk_fma_f32 v[188:189], v[188:189], v[200:201], v[196:197]
	v_pk_mul_f32 v[192:193], v[158:159], v[192:193] op_sel:[1,0]
	v_pk_mul_f32 v[194:195], v[158:159], v[194:195] op_sel:[1,0]
	v_pk_mul_f32 v[188:189], v[188:189], s[34:35] op_sel_hi:[1,0]
	v_pk_mul_f32 v[190:191], v[190:191], s[34:35] op_sel_hi:[1,0]
	v_pk_fma_f32 v[194:195], v[194:195], v[206:207], v[210:211]
	v_pk_fma_f32 v[192:193], v[192:193], v[204:205], v[208:209]
	v_pk_fma_f32 v[126:127], v[126:127], v[214:215], v[190:191]
	v_pk_fma_f32 v[124:125], v[124:125], v[212:213], v[188:189]
	flat_store_dwordx4 v[166:167], v[124:127]
	v_sub_f32_e32 v189, v225, v162
	v_sub_f32_e32 v188, v224, v162
	v_pk_mul_f32 v[124:125], v[192:193], s[34:35] op_sel_hi:[1,0]
	v_pk_mul_f32 v[126:127], v[194:195], s[34:35] op_sel_hi:[1,0]
	v_pk_fma_f32 v[120:121], v[120:121], v[216:217], v[124:125]
	v_pk_fma_f32 v[122:123], v[122:123], v[218:219], v[126:127]
	flat_store_dwordx4 v[166:167], v[120:123] offset:16
	v_sub_f32_e32 v125, v221, v162
	v_sub_f32_e32 v124, v220, v162
	v_sub_f32_e32 v123, v223, v162
	v_sub_f32_e32 v122, v222, v162
	v_pk_mul_f32 v[124:125], v[162:163], v[124:125] op_sel:[1,0]
	v_pk_mul_f32 v[122:123], v[162:163], v[122:123] op_sel:[1,0]
	v_pk_fma_f32 v[124:125], v[124:125], v[200:201], v[196:197]
	v_pk_fma_f32 v[122:123], v[122:123], v[202:203], v[198:199]
	v_sub_f32_e32 v127, v227, v162
	v_sub_f32_e32 v126, v226, v162
	v_lshl_add_u64 v[120:121], s[18:19], 0, v[250:251]
	v_pk_mul_f32 v[188:189], v[162:163], v[188:189] op_sel:[1,0]
	v_pk_mul_f32 v[126:127], v[162:163], v[126:127] op_sel:[1,0]
	v_pk_mul_f32 v[124:125], v[124:125], s[34:35] op_sel_hi:[1,0]
	v_pk_mul_f32 v[122:123], v[122:123], s[34:35] op_sel_hi:[1,0]
	v_lshl_add_u64 v[120:121], v[120:121], 0, v[168:169]
	v_pk_fma_f32 v[126:127], v[126:127], v[206:207], v[210:211]
	v_pk_fma_f32 v[188:189], v[188:189], v[204:205], v[208:209]
	v_pk_fma_f32 v[118:119], v[118:119], v[214:215], v[122:123]
	v_pk_fma_f32 v[116:117], v[116:117], v[212:213], v[124:125]
	flat_store_dwordx4 v[120:121], v[116:119]
	v_sub_f32_e32 v123, v233, v160
	v_sub_f32_e32 v122, v232, v160
; #define EPIRES_LOAD(q_, buf_) do { const int bj_ = (q_) >> 1, ai_ = (q_) & 1; \
;             _Pragma("unroll") for (int m = 0; m < 4; ++m) { const float* xp = Xin + (size_t)(row0 + ai_ * HALF + m * 16) * D + col0 + bj_ * HALF; xa[buf_][m] = *(const f32x4*)xp; xb[buf_][m] = *(const f32x4*)(xp + 4); } } while (0)
;     __device__ __forceinline__ void operator()(const f32x4 (&acc)[2][2][4][2], const Unit& u, int wr, int wc, int fr, int fq) const {
;     ...
;         EPIRES_LOAD(0, 0);
; #pragma unroll
;         for (int q = 0; q < 4; ++q) { const int bj = q >> 1, ai = q & 1, co = col0 + bj * HALF, cb = q & 1;
;             if (q + 1 < 4) EPIRES_LOAD(q + 1, cb ^ 1);
;             const f32x4 g0 = *(const f32x4*)(gp + bj * HALF), g1 = *(const f32x4*)(gp + bj * HALF + 4);
;             f32x4 w0 = {1.f, 1.f, 1.f, 1.f}, w1 = w0, b0 = {0.f, 0.f, 0.f, 0.f}, b1 = b0;
;             if (stats) { w0 = *(const f32x4*)(lw + co); w1 = *(const f32x4*)(lw + co + 4); b0 = *(const f32x4*)(lb + co); b1 = *(const f32x4*)(lb + co + 4); }
; #pragma unroll
;             for (int m = 0; m < 4; ++m) { float* op = Xout + (size_t)(row0 + ai * HALF + m * 16) * D + co;
;                 f32x4 x0 = xa[cb][m], x1 = xb[cb][m];
;                 if (stats) { x0 = (x0 - st[ai][m].x) * st[ai][m].y * w0 + b0; x1 = (x1 - st[ai][m].x) * st[ai][m].y * w1 + b1; }
;                 *(f32x4*)op = x0 * ALPHA + g0 * acc[ai][bj][m][0]; *(f32x4*)(op + 4) = x1 * ALPHA + g1 * acc[ai][bj][m][1]; } }
	v_pk_mul_f32 v[116:117], v[188:189], s[34:35] op_sel_hi:[1,0]
	v_pk_mul_f32 v[118:119], v[126:127], s[34:35] op_sel_hi:[1,0]
	v_pk_fma_f32 v[112:113], v[112:113], v[216:217], v[116:117]
	v_pk_fma_f32 v[114:115], v[114:115], v[218:219], v[118:119]
	flat_store_dwordx4 v[120:121], v[112:115] offset:16
	v_sub_f32_e32 v117, v229, v160
	v_sub_f32_e32 v116, v228, v160
	v_sub_f32_e32 v115, v231, v160
	v_sub_f32_e32 v114, v230, v160
	v_pk_mul_f32 v[116:117], v[160:161], v[116:117] op_sel:[1,0]
	v_pk_mul_f32 v[114:115], v[160:161], v[114:115] op_sel:[1,0]
	v_pk_fma_f32 v[116:117], v[116:117], v[200:201], v[196:197]
	v_pk_fma_f32 v[114:115], v[114:115], v[202:203], v[198:199]
	v_sub_f32_e32 v119, v235, v160
	v_sub_f32_e32 v118, v234, v160
	v_lshl_add_u64 v[112:113], s[18:19], 0, v[252:253]
	v_pk_mul_f32 v[122:123], v[160:161], v[122:123] op_sel:[1,0]
	v_pk_mul_f32 v[118:119], v[160:161], v[118:119] op_sel:[1,0]
	v_pk_mul_f32 v[116:117], v[116:117], s[34:35] op_sel_hi:[1,0]
	v_pk_mul_f32 v[114:115], v[114:115], s[34:35] op_sel_hi:[1,0]
	v_lshl_add_u64 v[112:113], v[112:113], 0, v[168:169]
	v_pk_fma_f32 v[118:119], v[118:119], v[206:207], v[210:211]
	v_pk_fma_f32 v[122:123], v[122:123], v[204:205], v[208:209]
	v_pk_fma_f32 v[110:111], v[110:111], v[214:215], v[114:115]
	v_pk_fma_f32 v[108:109], v[108:109], v[212:213], v[116:117]
	flat_store_dwordx4 v[112:113], v[108:111]
	v_sub_f32_e32 v115, v241, v156
	v_sub_f32_e32 v114, v240, v156
	v_pk_mul_f32 v[108:109], v[122:123], s[34:35] op_sel_hi:[1,0]
	v_pk_mul_f32 v[110:111], v[118:119], s[34:35] op_sel_hi:[1,0]
	v_pk_fma_f32 v[104:105], v[104:105], v[216:217], v[108:109]
	v_pk_fma_f32 v[106:107], v[106:107], v[218:219], v[110:111]
	flat_store_dwordx4 v[112:113], v[104:107] offset:16
	v_sub_f32_e32 v109, v237, v156
	v_sub_f32_e32 v108, v236, v156
	v_sub_f32_e32 v107, v239, v156
	v_sub_f32_e32 v106, v238, v156
	v_pk_mul_f32 v[108:109], v[156:157], v[108:109] op_sel:[1,0]
	v_pk_mul_f32 v[106:107], v[156:157], v[106:107] op_sel:[1,0]
	v_pk_fma_f32 v[108:109], v[108:109], v[200:201], v[196:197]
	v_pk_fma_f32 v[106:107], v[106:107], v[202:203], v[198:199]
	v_sub_f32_e32 v111, v243, v156
	v_sub_f32_e32 v110, v242, v156
	v_lshl_add_u64 v[104:105], s[18:19], 0, v[248:249]
	v_pk_mul_f32 v[114:115], v[156:157], v[114:115] op_sel:[1,0]
	v_pk_mul_f32 v[110:111], v[156:157], v[110:111] op_sel:[1,0]
	v_pk_mul_f32 v[108:109], v[108:109], s[34:35] op_sel_hi:[1,0]
	v_pk_mul_f32 v[106:107], v[106:107], s[34:35] op_sel_hi:[1,0]
	v_lshl_add_u64 v[104:105], v[104:105], 0, v[168:169]
	v_pk_fma_f32 v[110:111], v[110:111], v[206:207], v[210:211]
	v_pk_fma_f32 v[114:115], v[114:115], v[204:205], v[208:209]
	v_pk_fma_f32 v[102:103], v[102:103], v[214:215], v[106:107]
	v_pk_fma_f32 v[100:101], v[100:101], v[212:213], v[108:109]
	flat_store_dwordx4 v[104:105], v[100:103]
	v_lshl_add_u64 v[118:119], v[178:179], 0, s[30:31]
	v_lshl_add_u64 v[126:127], v[178:179], 0, s[14:15]
	v_pk_mul_f32 v[100:101], v[114:115], s[34:35] op_sel_hi:[1,0]
	v_pk_mul_f32 v[102:103], v[110:111], s[34:35] op_sel_hi:[1,0]
	v_pk_fma_f32 v[96:97], v[96:97], v[216:217], v[100:101]
	v_pk_fma_f32 v[98:99], v[98:99], v[218:219], v[102:103]
	flat_store_dwordx4 v[104:105], v[96:99] offset:16
	flat_load_dwordx4 v[106:109], v[146:147]
	flat_load_dwordx4 v[114:117], v[148:149]
	flat_load_dwordx4 v[122:125], v[154:155] offset:16
	flat_load_dwordx4 v[188:191], v[146:147] offset:16
	flat_load_dwordx4 v[192:195], v[148:149] offset:16
	flat_load_dwordx4 v[196:199], v[150:151]
	flat_load_dwordx4 v[200:203], v[150:151] offset:16
	v_lshl_add_u64 v[110:111], v[178:179], 0, s[28:29]
	v_lshl_add_u64 v[98:99], v[176:177], 0, v[110:111]
	flat_load_dwordx4 v[204:207], v[98:99]
	flat_load_dwordx4 v[208:211], v[98:99] offset:16
	v_lshl_add_u64 v[100:101], v[176:177], 0, v[118:119]
	flat_load_dwordx4 v[212:215], v[100:101]
	flat_load_dwordx4 v[216:219], v[100:101] offset:16
	v_lshl_add_u64 v[102:103], v[176:177], 0, v[126:127]
	flat_load_dwordx4 v[176:179], v[102:103]
	flat_load_dwordx4 v[220:223], v[102:103] offset:16
	flat_load_dwordx4 v[224:227], v[164:165] offset:512
	v_lshl_add_u64 v[96:97], s[18:19], 0, v[180:181]
	v_sub_f32_e32 v181, v245, v152
	v_sub_f32_e32 v180, v244, v152
	v_sub_f32_e32 v229, v247, v152
	v_sub_f32_e32 v228, v246, v152
	v_pk_mul_f32 v[228:229], v[152:153], v[228:229] op_sel:[1,0]
	v_pk_mul_f32 v[180:181], v[152:153], v[180:181] op_sel:[1,0]
	v_lshl_add_u64 v[96:97], v[96:97], 0, v[168:169]
	s_waitcnt vmcnt(0) lgkmcnt(0)
; #define EPIRES_LOAD(q_, buf_) do { const int bj_ = (q_) >> 1, ai_ = (q_) & 1; \
;             _Pragma("unroll") for (int m = 0; m < 4; ++m) { const float* xp = Xin + (size_t)(row0 + ai_ * HALF + m * 16) * D + col0 + bj_ * HALF; xa[buf_][m] = *(const f32x4*)xp; xb[buf_][m] = *(const f32x4*)(xp + 4); } } while (0)
;     __device__ __forceinline__ void operator()(const f32x4 (&acc)[2][2][4][2], const Unit& u, int wr, int wc, int fr, int fq) const {
;     ...
;         EPIRES_LOAD(0, 0);
; #pragma unroll
;         for (int q = 0; q < 4; ++q) { const int bj = q >> 1, ai = q & 1, co = col0 + bj * HALF, cb = q & 1;
;             if (q + 1 < 4) EPIRES_LOAD(q + 1, cb ^ 1);
;             const f32x4 g0 = *(const f32x4*)(gp + bj * HALF), g1 = *(const f32x4*)(gp + bj * HALF + 4);
;             f32x4 w0 = {1.f, 1.f, 1.f, 1.f}, w1 = w0, b0 = {0.f, 0.f, 0.f, 0.f}, b1 = b0;
;             if (stats) { w0 = *(const f32x4*)(lw + co); w1 = *(const f32x4*)(lw + co + 4); b0 = *(const f32x4*)(lb + co); b1 = *(const f32x4*)(lb + co + 4); }
; #pragma unroll
;             for (int m = 0; m < 4; ++m) { float* op = Xout + (size_t)(row0 + ai * HALF + m * 16) * D + co;
;                 f32x4 x0 = xa[cb][m], x1 = xb[cb][m];
;                 if (stats) { x0 = (x0 - st[ai][m].x) * st[ai][m].y * w0 + b0; x1 = (x1 - st[ai][m].x) * st[ai][m].y * w1 + b1; }
;                 *(f32x4*)op = x0 * ALPHA + g0 * acc[ai][bj][m][0]; *(f32x4*)(op + 4) = x1 * ALPHA + g1 * acc[ai][bj][m][1]; } }
	v_pk_fma_f32 v[180:181], v[180:181], v[106:107], v[114:115]
	v_pk_fma_f32 v[228:229], v[228:229], v[108:109], v[116:117]
	v_sub_f32_e32 v123, v123, v152
	v_sub_f32_e32 v122, v122, v152
	v_sub_f32_e32 v125, v125, v152
	v_sub_f32_e32 v124, v124, v152
	v_pk_mul_f32 v[124:125], v[152:153], v[124:125] op_sel:[1,0]
	v_pk_mul_f32 v[122:123], v[152:153], v[122:123] op_sel:[1,0]
	v_pk_mul_f32 v[228:229], v[228:229], s[34:35] op_sel_hi:[1,0]
	v_pk_mul_f32 v[180:181], v[180:181], s[34:35] op_sel_hi:[1,0]
	v_pk_fma_f32 v[122:123], v[122:123], v[188:189], v[192:193]
	v_pk_fma_f32 v[124:125], v[124:125], v[190:191], v[194:195]
	v_pk_fma_f32 v[92:93], v[92:93], v[196:197], v[180:181]
	v_pk_fma_f32 v[94:95], v[94:95], v[198:199], v[228:229]
	flat_store_dwordx4 v[96:97], v[92:95]
	s_nop 1
	v_pk_mul_f32 v[92:93], v[124:125], s[34:35] op_sel_hi:[1,0]
	v_pk_mul_f32 v[94:95], v[122:123], s[34:35] op_sel_hi:[1,0]
	v_pk_fma_f32 v[90:91], v[90:91], v[202:203], v[92:93]
	v_pk_fma_f32 v[88:89], v[88:89], v[200:201], v[94:95]
	flat_store_dwordx4 v[96:97], v[88:91] offset:16
	v_sub_f32_e32 v93, v207, v144
	v_sub_f32_e32 v92, v206, v144
	v_sub_f32_e32 v91, v205, v144
	v_sub_f32_e32 v90, v204, v144
	v_pk_mul_f32 v[92:93], v[144:145], v[92:93] op_sel:[1,0]
	v_pk_mul_f32 v[90:91], v[144:145], v[90:91] op_sel:[1,0]
	v_lshl_add_u64 v[88:89], s[18:19], 0, v[110:111]
	v_pk_fma_f32 v[90:91], v[90:91], v[106:107], v[114:115]
	v_pk_fma_f32 v[92:93], v[92:93], v[108:109], v[116:117]
	v_sub_f32_e32 v95, v209, v144
	v_sub_f32_e32 v94, v208, v144
	v_sub_f32_e32 v111, v211, v144
	v_sub_f32_e32 v110, v210, v144
	v_pk_mul_f32 v[110:111], v[144:145], v[110:111] op_sel:[1,0]
	v_pk_mul_f32 v[94:95], v[144:145], v[94:95] op_sel:[1,0]
	v_pk_mul_f32 v[92:93], v[92:93], s[34:35] op_sel_hi:[1,0]
	v_pk_mul_f32 v[90:91], v[90:91], s[34:35] op_sel_hi:[1,0]
	v_lshl_add_u64 v[88:89], v[88:89], 0, v[168:169]
	v_pk_fma_f32 v[94:95], v[94:95], v[188:189], v[192:193]
	v_pk_fma_f32 v[110:111], v[110:111], v[190:191], v[194:195]
	v_pk_fma_f32 v[84:85], v[84:85], v[196:197], v[90:91]
	v_pk_fma_f32 v[86:87], v[86:87], v[198:199], v[92:93]
	flat_store_dwordx4 v[88:89], v[84:87]
	v_sub_f32_e32 v91, v219, v142
	v_sub_f32_e32 v90, v218, v142
	v_pk_mul_f32 v[84:85], v[110:111], s[34:35] op_sel_hi:[1,0]
	v_pk_mul_f32 v[86:87], v[94:95], s[34:35] op_sel_hi:[1,0]
	v_pk_fma_f32 v[82:83], v[82:83], v[202:203], v[84:85]
	v_pk_fma_f32 v[80:81], v[80:81], v[200:201], v[86:87]
	flat_store_dwordx4 v[88:89], v[80:83] offset:16
	v_sub_f32_e32 v85, v215, v142
	v_sub_f32_e32 v84, v214, v142
	v_sub_f32_e32 v83, v213, v142
	v_sub_f32_e32 v82, v212, v142
	v_pk_mul_f32 v[84:85], v[142:143], v[84:85] op_sel:[1,0]
	v_pk_mul_f32 v[82:83], v[142:143], v[82:83] op_sel:[1,0]
	v_pk_fma_f32 v[84:85], v[84:85], v[108:109], v[116:117]
	v_pk_fma_f32 v[82:83], v[82:83], v[106:107], v[114:115]
	v_sub_f32_e32 v87, v217, v142
	v_sub_f32_e32 v86, v216, v142
	v_lshl_add_u64 v[80:81], s[18:19], 0, v[118:119]
	v_pk_mul_f32 v[90:91], v[142:143], v[90:91] op_sel:[1,0]
	v_pk_mul_f32 v[86:87], v[142:143], v[86:87] op_sel:[1,0]
	v_pk_mul_f32 v[84:85], v[84:85], s[34:35] op_sel_hi:[1,0]
	v_pk_mul_f32 v[82:83], v[82:83], s[34:35] op_sel_hi:[1,0]
	v_lshl_add_u64 v[80:81], v[80:81], 0, v[168:169]
	v_pk_fma_f32 v[86:87], v[86:87], v[188:189], v[192:193]
	v_pk_fma_f32 v[90:91], v[90:91], v[190:191], v[194:195]
	v_pk_fma_f32 v[76:77], v[76:77], v[196:197], v[82:83]
	v_pk_fma_f32 v[78:79], v[78:79], v[198:199], v[84:85]
	flat_store_dwordx4 v[80:81], v[76:79]
	v_sub_f32_e32 v83, v223, v140
	v_sub_f32_e32 v82, v222, v140
	v_pk_mul_f32 v[76:77], v[90:91], s[34:35] op_sel_hi:[1,0]
	v_pk_mul_f32 v[78:79], v[86:87], s[34:35] op_sel_hi:[1,0]
	v_pk_fma_f32 v[74:75], v[74:75], v[202:203], v[76:77]
	v_pk_fma_f32 v[72:73], v[72:73], v[200:201], v[78:79]
	flat_store_dwordx4 v[80:81], v[72:75] offset:16
	v_sub_f32_e32 v77, v179, v140
	v_sub_f32_e32 v76, v178, v140
	v_sub_f32_e32 v75, v177, v140
	v_sub_f32_e32 v74, v176, v140
	v_pk_mul_f32 v[76:77], v[140:141], v[76:77] op_sel:[1,0]
	v_pk_mul_f32 v[74:75], v[140:141], v[74:75] op_sel:[1,0]
	v_pk_fma_f32 v[76:77], v[76:77], v[108:109], v[116:117]
	v_pk_fma_f32 v[74:75], v[74:75], v[106:107], v[114:115]
	v_sub_f32_e32 v79, v221, v140
	v_sub_f32_e32 v78, v220, v140
	v_lshl_add_u64 v[72:73], s[18:19], 0, v[126:127]
	v_pk_mul_f32 v[82:83], v[140:141], v[82:83] op_sel:[1,0]
	v_pk_mul_f32 v[78:79], v[140:141], v[78:79] op_sel:[1,0]
	v_pk_mul_f32 v[76:77], v[76:77], s[34:35] op_sel_hi:[1,0]
	v_pk_mul_f32 v[74:75], v[74:75], s[34:35] op_sel_hi:[1,0]
	v_lshl_add_u64 v[72:73], v[72:73], 0, v[168:169]
	v_pk_fma_f32 v[78:79], v[78:79], v[188:189], v[192:193]
	v_pk_fma_f32 v[82:83], v[82:83], v[190:191], v[194:195]
	v_pk_fma_f32 v[68:69], v[68:69], v[196:197], v[74:75]
	v_pk_fma_f32 v[70:71], v[70:71], v[198:199], v[76:77]
	flat_store_dwordx4 v[72:73], v[68:71]
	v_sub_f32_e32 v87, v227, v158
	v_sub_f32_e32 v86, v226, v158
	v_pk_mul_f32 v[68:69], v[82:83], s[34:35] op_sel_hi:[1,0]
	v_pk_mul_f32 v[70:71], v[78:79], s[34:35] op_sel_hi:[1,0]
	v_pk_fma_f32 v[66:67], v[66:67], v[202:203], v[68:69]
	v_pk_fma_f32 v[64:65], v[64:65], v[200:201], v[70:71]
	flat_store_dwordx4 v[72:73], v[64:67] offset:16
	flat_load_dwordx4 v[200:203], v[154:155] offset:512
	flat_load_dwordx4 v[204:207], v[154:155] offset:528
	flat_load_dwordx4 v[208:211], v[98:99] offset:512
	flat_load_dwordx4 v[212:215], v[98:99] offset:528
	flat_load_dwordx4 v[216:219], v[100:101] offset:512
	flat_load_dwordx4 v[220:223], v[100:101] offset:528
	flat_load_dwordx4 v[226:229], v[102:103] offset:512
	flat_load_dwordx4 v[230:233], v[102:103] offset:528
	flat_load_dwordx4 v[64:67], v[146:147] offset:512
	s_nop 0
	flat_load_dwordx4 v[68:71], v[148:149] offset:512
	flat_load_dwordx4 v[74:77], v[164:165] offset:528
	flat_load_dwordx4 v[82:85], v[146:147] offset:528
	flat_load_dwordx4 v[90:93], v[148:149] offset:528
	flat_load_dwordx4 v[106:109], v[150:151] offset:512
	flat_load_dwordx4 v[114:117], v[150:151] offset:528
	flat_load_dwordx4 v[122:125], v[170:171] offset:512
	s_nop 0
	flat_load_dwordx4 v[168:171], v[170:171] offset:528
	s_nop 0
	flat_load_dwordx4 v[176:179], v[172:173] offset:512
	flat_load_dwordx4 v[188:191], v[172:173] offset:528
	flat_load_dwordx4 v[192:195], v[174:175] offset:512
	s_nop 0
	flat_load_dwordx4 v[172:175], v[174:175] offset:528
	s_nop 0
	v_sub_f32_e32 v79, v225, v158
	v_sub_f32_e32 v78, v224, v158
	v_pk_mul_f32 v[86:87], v[158:159], v[86:87] op_sel:[1,0]
	v_pk_mul_f32 v[78:79], v[158:159], v[78:79] op_sel:[1,0]
	s_waitcnt vmcnt(0) lgkmcnt(0)
; #define EPIRES_LOAD(q_, buf_) do { const int bj_ = (q_) >> 1, ai_ = (q_) & 1; \
;             _Pragma("unroll") for (int m = 0; m < 4; ++m) { const float* xp = Xin + (size_t)(row0 + ai_ * HALF + m * 16) * D + col0 + bj_ * HALF; xa[buf_][m] = *(const f32x4*)xp; xb[buf_][m] = *(const f32x4*)(xp + 4); } } while (0)
;     __device__ __forceinline__ void operator()(const f32x4 (&acc)[2][2][4][2], const Unit& u, int wr, int wc, int fr, int fq) const {
;     ...
;         EPIRES_LOAD(0, 0);
; #pragma unroll
;         for (int q = 0; q < 4; ++q) { const int bj = q >> 1, ai = q & 1, co = col0 + bj * HALF, cb = q & 1;
;             if (q + 1 < 4) EPIRES_LOAD(q + 1, cb ^ 1);
;             const f32x4 g0 = *(const f32x4*)(gp + bj * HALF), g1 = *(const f32x4*)(gp + bj * HALF + 4);
;             f32x4 w0 = {1.f, 1.f, 1.f, 1.f}, w1 = w0, b0 = {0.f, 0.f, 0.f, 0.f}, b1 = b0;
;             if (stats) { w0 = *(const f32x4*)(lw + co); w1 = *(const f32x4*)(lw + co + 4); b0 = *(const f32x4*)(lb + co); b1 = *(const f32x4*)(lb + co + 4); }
; #pragma unroll
;             for (int m = 0; m < 4; ++m) { float* op = Xout + (size_t)(row0 + ai * HALF + m * 16) * D + co;
;                 f32x4 x0 = xa[cb][m], x1 = xb[cb][m];
;                 if (stats) { x0 = (x0 - st[ai][m].x) * st[ai][m].y * w0 + b0; x1 = (x1 - st[ai][m].x) * st[ai][m].y * w1 + b1; }
;                 *(f32x4*)op = x0 * ALPHA + g0 * acc[ai][bj][m][0]; *(f32x4*)(op + 4) = x1 * ALPHA + g1 * acc[ai][bj][m][1]; } }
	v_mov_b32_e32 v196, v200
	v_mov_b32_e32 v197, v201
	v_mov_b32_e32 v198, v202
	v_mov_b32_e32 v199, v203
	v_pk_fma_f32 v[86:87], v[86:87], v[66:67], v[70:71]
	v_pk_fma_f32 v[78:79], v[78:79], v[64:65], v[68:69]
	v_sub_f32_e32 v75, v75, v158
	v_sub_f32_e32 v74, v74, v158
	v_sub_f32_e32 v77, v77, v158
	v_sub_f32_e32 v76, v76, v158
	v_pk_mul_f32 v[76:77], v[158:159], v[76:77] op_sel:[1,0]
	v_pk_mul_f32 v[74:75], v[158:159], v[74:75] op_sel:[1,0]
	v_pk_mul_f32 v[86:87], v[86:87], s[34:35] op_sel_hi:[1,0]
	v_pk_mul_f32 v[78:79], v[78:79], s[34:35] op_sel_hi:[1,0]
	v_pk_fma_f32 v[74:75], v[74:75], v[82:83], v[90:91]
	v_pk_fma_f32 v[76:77], v[76:77], v[84:85], v[92:93]
	v_pk_fma_f32 v[60:61], v[60:61], v[106:107], v[78:79]
	v_pk_fma_f32 v[62:63], v[62:63], v[108:109], v[86:87]
	flat_store_dwordx4 v[166:167], v[60:63] offset:512
	v_sub_f32_e32 v79, v197, v152
	v_sub_f32_e32 v78, v196, v152
	v_pk_mul_f32 v[60:61], v[76:77], s[34:35] op_sel_hi:[1,0]
	v_pk_mul_f32 v[62:63], v[74:75], s[34:35] op_sel_hi:[1,0]
	v_pk_fma_f32 v[58:59], v[58:59], v[116:117], v[60:61]
	v_pk_fma_f32 v[56:57], v[56:57], v[114:115], v[62:63]
	flat_store_dwordx4 v[166:167], v[56:59] offset:528
	v_sub_f32_e32 v61, v169, v162
	v_sub_f32_e32 v60, v168, v162
	v_sub_f32_e32 v57, v123, v162
	v_sub_f32_e32 v56, v122, v162
	v_sub_f32_e32 v59, v125, v162
	v_sub_f32_e32 v58, v124, v162
	v_pk_mul_f32 v[58:59], v[162:163], v[58:59] op_sel:[1,0]
	v_pk_mul_f32 v[56:57], v[162:163], v[56:57] op_sel:[1,0]
	v_pk_fma_f32 v[58:59], v[58:59], v[66:67], v[70:71]
	v_pk_fma_f32 v[56:57], v[56:57], v[64:65], v[68:69]
	v_sub_f32_e32 v63, v171, v162
	v_sub_f32_e32 v62, v170, v162
	v_pk_mul_f32 v[62:63], v[162:163], v[62:63] op_sel:[1,0]
	v_pk_mul_f32 v[60:61], v[162:163], v[60:61] op_sel:[1,0]
	v_pk_mul_f32 v[58:59], v[58:59], s[34:35] op_sel_hi:[1,0]
	v_pk_mul_f32 v[56:57], v[56:57], s[34:35] op_sel_hi:[1,0]
	v_pk_fma_f32 v[60:61], v[60:61], v[82:83], v[90:91]
	v_pk_fma_f32 v[62:63], v[62:63], v[84:85], v[92:93]
	v_pk_fma_f32 v[52:53], v[52:53], v[106:107], v[56:57]
	v_pk_fma_f32 v[54:55], v[54:55], v[108:109], v[58:59]
	flat_store_dwordx4 v[120:121], v[52:55] offset:512
	v_sub_f32_e32 v87, v199, v152
	v_sub_f32_e32 v86, v198, v152
	v_pk_mul_f32 v[52:53], v[62:63], s[34:35] op_sel_hi:[1,0]
	v_pk_mul_f32 v[54:55], v[60:61], s[34:35] op_sel_hi:[1,0]
	v_pk_fma_f32 v[50:51], v[50:51], v[116:117], v[52:53]
	v_pk_fma_f32 v[48:49], v[48:49], v[114:115], v[54:55]
	flat_store_dwordx4 v[120:121], v[48:51] offset:528
	v_sub_f32_e32 v53, v189, v160
	v_sub_f32_e32 v52, v188, v160
	v_sub_f32_e32 v49, v177, v160
	v_sub_f32_e32 v48, v176, v160
	v_sub_f32_e32 v51, v179, v160
	v_sub_f32_e32 v50, v178, v160
	v_pk_mul_f32 v[50:51], v[160:161], v[50:51] op_sel:[1,0]
	v_pk_mul_f32 v[48:49], v[160:161], v[48:49] op_sel:[1,0]
	v_pk_fma_f32 v[50:51], v[50:51], v[66:67], v[70:71]
	v_pk_fma_f32 v[48:49], v[48:49], v[64:65], v[68:69]
	v_sub_f32_e32 v55, v191, v160
	v_sub_f32_e32 v54, v190, v160
	v_pk_mul_f32 v[54:55], v[160:161], v[54:55] op_sel:[1,0]
	v_pk_mul_f32 v[52:53], v[160:161], v[52:53] op_sel:[1,0]
	v_pk_mul_f32 v[50:51], v[50:51], s[34:35] op_sel_hi:[1,0]
	v_pk_mul_f32 v[48:49], v[48:49], s[34:35] op_sel_hi:[1,0]
	v_pk_fma_f32 v[52:53], v[52:53], v[82:83], v[90:91]
	v_pk_fma_f32 v[54:55], v[54:55], v[84:85], v[92:93]
	v_pk_fma_f32 v[44:45], v[44:45], v[106:107], v[48:49]
	v_pk_fma_f32 v[46:47], v[46:47], v[108:109], v[50:51]
	flat_store_dwordx4 v[112:113], v[44:47] offset:512
	v_pk_mul_f32 v[86:87], v[152:153], v[86:87] op_sel:[1,0]
	v_pk_mul_f32 v[78:79], v[152:153], v[78:79] op_sel:[1,0]
	v_pk_mul_f32 v[44:45], v[54:55], s[34:35] op_sel_hi:[1,0]
	v_pk_mul_f32 v[46:47], v[52:53], s[34:35] op_sel_hi:[1,0]
	v_pk_fma_f32 v[42:43], v[42:43], v[116:117], v[44:45]
	v_pk_fma_f32 v[40:41], v[40:41], v[114:115], v[46:47]
	flat_store_dwordx4 v[112:113], v[40:43] offset:528
	v_sub_f32_e32 v45, v173, v156
	v_sub_f32_e32 v44, v172, v156
	v_sub_f32_e32 v41, v193, v156
	v_sub_f32_e32 v40, v192, v156
	v_sub_f32_e32 v43, v195, v156
	v_sub_f32_e32 v42, v194, v156
	v_pk_mul_f32 v[42:43], v[156:157], v[42:43] op_sel:[1,0]
	v_pk_mul_f32 v[40:41], v[156:157], v[40:41] op_sel:[1,0]
	v_pk_fma_f32 v[42:43], v[42:43], v[66:67], v[70:71]
	v_pk_fma_f32 v[40:41], v[40:41], v[64:65], v[68:69]
	v_sub_f32_e32 v47, v175, v156
	v_sub_f32_e32 v46, v174, v156
	v_pk_mul_f32 v[46:47], v[156:157], v[46:47] op_sel:[1,0]
	v_pk_mul_f32 v[44:45], v[156:157], v[44:45] op_sel:[1,0]
	v_pk_mul_f32 v[42:43], v[42:43], s[34:35] op_sel_hi:[1,0]
	v_pk_mul_f32 v[40:41], v[40:41], s[34:35] op_sel_hi:[1,0]
	v_pk_fma_f32 v[44:45], v[44:45], v[82:83], v[90:91]
	v_pk_fma_f32 v[46:47], v[46:47], v[84:85], v[92:93]
	v_pk_fma_f32 v[36:37], v[36:37], v[106:107], v[40:41]
	v_pk_fma_f32 v[38:39], v[38:39], v[108:109], v[42:43]
	flat_store_dwordx4 v[104:105], v[36:39] offset:512
	s_nop 1
	v_pk_mul_f32 v[36:37], v[46:47], s[34:35] op_sel_hi:[1,0]
	v_pk_mul_f32 v[38:39], v[44:45], s[34:35] op_sel_hi:[1,0]
	v_pk_fma_f32 v[34:35], v[34:35], v[116:117], v[36:37]
	v_pk_fma_f32 v[32:33], v[32:33], v[114:115], v[38:39]
	flat_store_dwordx4 v[104:105], v[32:35] offset:528
	flat_load_dwordx4 v[32:35], v[146:147] offset:512
	s_nop 0
	flat_load_dwordx4 v[36:39], v[148:149] offset:512
	flat_load_dwordx4 v[44:47], v[146:147] offset:528
	flat_load_dwordx4 v[48:51], v[148:149] offset:528
	flat_load_dwordx4 v[52:55], v[150:151] offset:512
	flat_load_dwordx4 v[56:59], v[150:151] offset:528
	s_waitcnt vmcnt(0) lgkmcnt(0)
; #define EPIRES_LOAD(q_, buf_) do { const int bj_ = (q_) >> 1, ai_ = (q_) & 1; \
;             _Pragma("unroll") for (int m = 0; m < 4; ++m) { const float* xp = Xin + (size_t)(row0 + ai_ * HALF + m * 16) * D + col0 + bj_ * HALF; xa[buf_][m] = *(const f32x4*)xp; xb[buf_][m] = *(const f32x4*)(xp + 4); } } while (0)
;     __device__ __forceinline__ void operator()(const f32x4 (&acc)[2][2][4][2], const Unit& u, int wr, int wc, int fr, int fq) const {
;     ...
;         for (int q = 0; q < 4; ++q) { const int bj = q >> 1, ai = q & 1, co = col0 + bj * HALF, cb = q & 1;
;             if (q + 1 < 4) EPIRES_LOAD(q + 1, cb ^ 1);
;             const f32x4 g0 = *(const f32x4*)(gp + bj * HALF), g1 = *(const f32x4*)(gp + bj * HALF + 4);
;             f32x4 w0 = {1.f, 1.f, 1.f, 1.f}, w1 = w0, b0 = {0.f, 0.f, 0.f, 0.f}, b1 = b0;
;             if (stats) { w0 = *(const f32x4*)(lw + co); w1 = *(const f32x4*)(lw + co + 4); b0 = *(const f32x4*)(lb + co); b1 = *(const f32x4*)(lb + co + 4); }
; #pragma unroll
;             for (int m = 0; m < 4; ++m) { float* op = Xout + (size_t)(row0 + ai * HALF + m * 16) * D + co;
;                 f32x4 x0 = xa[cb][m], x1 = xb[cb][m];
;                 if (stats) { x0 = (x0 - st[ai][m].x) * st[ai][m].y * w0 + b0; x1 = (x1 - st[ai][m].x) * st[ai][m].y * w1 + b1; }
;                 *(f32x4*)op = x0 * ALPHA + g0 * acc[ai][bj][m][0]; *(f32x4*)(op + 4) = x1 * ALPHA + g1 * acc[ai][bj][m][1]; } }
	v_mov_b32_e32 v40, v204
	v_mov_b32_e32 v41, v205
	v_mov_b32_e32 v42, v206
	v_mov_b32_e32 v43, v207
	v_mov_b32_e32 v60, v208
	v_mov_b32_e32 v61, v209
	v_mov_b32_e32 v62, v210
	v_mov_b32_e32 v63, v211
	v_mov_b32_e32 v64, v212
	v_mov_b32_e32 v65, v213
	v_mov_b32_e32 v66, v214
	v_mov_b32_e32 v67, v215
	v_mov_b32_e32 v68, v216
	v_mov_b32_e32 v69, v217
	v_mov_b32_e32 v70, v218
	v_mov_b32_e32 v71, v219
	v_mov_b32_e32 v74, v220
	v_mov_b32_e32 v75, v221
	v_mov_b32_e32 v76, v222
	v_mov_b32_e32 v77, v223
	v_mov_b32_e32 v82, v226
	v_mov_b32_e32 v83, v227
	v_mov_b32_e32 v84, v228
	v_mov_b32_e32 v85, v229
	v_mov_b32_e32 v90, v230
	v_mov_b32_e32 v91, v231
	v_mov_b32_e32 v92, v232
	v_mov_b32_e32 v93, v233
	v_pk_fma_f32 v[78:79], v[78:79], v[32:33], v[36:37]
	v_pk_fma_f32 v[86:87], v[86:87], v[34:35], v[38:39]
	v_sub_f32_e32 v41, v41, v152
	v_sub_f32_e32 v40, v40, v152
	v_sub_f32_e32 v43, v43, v152
	v_sub_f32_e32 v42, v42, v152
	v_pk_mul_f32 v[42:43], v[152:153], v[42:43] op_sel:[1,0]
	v_pk_mul_f32 v[40:41], v[152:153], v[40:41] op_sel:[1,0]
	v_pk_mul_f32 v[86:87], v[86:87], s[34:35] op_sel_hi:[1,0]
	v_pk_mul_f32 v[78:79], v[78:79], s[34:35] op_sel_hi:[1,0]
	v_pk_fma_f32 v[40:41], v[40:41], v[44:45], v[48:49]
	v_pk_fma_f32 v[42:43], v[42:43], v[46:47], v[50:51]
	v_pk_fma_f32 v[28:29], v[28:29], v[52:53], v[78:79]
	v_pk_fma_f32 v[30:31], v[30:31], v[54:55], v[86:87]
	flat_store_dwordx4 v[96:97], v[28:31] offset:512
	s_nop 1
	v_pk_mul_f32 v[28:29], v[42:43], s[34:35] op_sel_hi:[1,0]
	v_pk_mul_f32 v[30:31], v[40:41], s[34:35] op_sel_hi:[1,0]
	v_pk_fma_f32 v[26:27], v[26:27], v[58:59], v[28:29]
	v_pk_fma_f32 v[24:25], v[24:25], v[56:57], v[30:31]
	flat_store_dwordx4 v[96:97], v[24:27] offset:528
	v_sub_f32_e32 v29, v65, v144
	v_sub_f32_e32 v28, v64, v144
	v_sub_f32_e32 v25, v61, v144
	v_sub_f32_e32 v24, v60, v144
	v_sub_f32_e32 v27, v63, v144
	v_sub_f32_e32 v26, v62, v144
	v_pk_mul_f32 v[26:27], v[144:145], v[26:27] op_sel:[1,0]
	v_pk_mul_f32 v[24:25], v[144:145], v[24:25] op_sel:[1,0]
	v_pk_fma_f32 v[26:27], v[26:27], v[34:35], v[38:39]
	v_pk_fma_f32 v[24:25], v[24:25], v[32:33], v[36:37]
	v_sub_f32_e32 v31, v67, v144
	v_sub_f32_e32 v30, v66, v144
	v_pk_mul_f32 v[30:31], v[144:145], v[30:31] op_sel:[1,0]
	v_pk_mul_f32 v[28:29], v[144:145], v[28:29] op_sel:[1,0]
	v_pk_mul_f32 v[26:27], v[26:27], s[34:35] op_sel_hi:[1,0]
	v_pk_mul_f32 v[24:25], v[24:25], s[34:35] op_sel_hi:[1,0]
	v_pk_fma_f32 v[28:29], v[28:29], v[44:45], v[48:49]
	v_pk_fma_f32 v[30:31], v[30:31], v[46:47], v[50:51]
	v_pk_fma_f32 v[20:21], v[20:21], v[52:53], v[24:25]
	v_pk_fma_f32 v[22:23], v[22:23], v[54:55], v[26:27]
	flat_store_dwordx4 v[88:89], v[20:23] offset:512
	s_nop 1
	v_pk_mul_f32 v[20:21], v[30:31], s[34:35] op_sel_hi:[1,0]
	v_pk_mul_f32 v[22:23], v[28:29], s[34:35] op_sel_hi:[1,0]
	v_pk_fma_f32 v[18:19], v[18:19], v[58:59], v[20:21]
	v_pk_fma_f32 v[16:17], v[16:17], v[56:57], v[22:23]
	flat_store_dwordx4 v[88:89], v[16:19] offset:528
	v_sub_f32_e32 v21, v75, v142
	v_sub_f32_e32 v20, v74, v142
	v_sub_f32_e32 v17, v69, v142
	v_sub_f32_e32 v16, v68, v142
	v_sub_f32_e32 v19, v71, v142
	v_sub_f32_e32 v18, v70, v142
	v_pk_mul_f32 v[18:19], v[142:143], v[18:19] op_sel:[1,0]
	v_pk_mul_f32 v[16:17], v[142:143], v[16:17] op_sel:[1,0]
	v_pk_fma_f32 v[18:19], v[18:19], v[34:35], v[38:39]
	v_pk_fma_f32 v[16:17], v[16:17], v[32:33], v[36:37]
	v_sub_f32_e32 v23, v77, v142
	v_sub_f32_e32 v22, v76, v142
	v_pk_mul_f32 v[22:23], v[142:143], v[22:23] op_sel:[1,0]
	v_pk_mul_f32 v[20:21], v[142:143], v[20:21] op_sel:[1,0]
	v_pk_mul_f32 v[18:19], v[18:19], s[34:35] op_sel_hi:[1,0]
	v_pk_mul_f32 v[16:17], v[16:17], s[34:35] op_sel_hi:[1,0]
	v_pk_fma_f32 v[20:21], v[20:21], v[44:45], v[48:49]
	v_pk_fma_f32 v[22:23], v[22:23], v[46:47], v[50:51]
	v_pk_fma_f32 v[12:13], v[12:13], v[52:53], v[16:17]
	v_pk_fma_f32 v[14:15], v[14:15], v[54:55], v[18:19]
	flat_store_dwordx4 v[80:81], v[12:15] offset:512
	s_nop 1
	v_pk_mul_f32 v[12:13], v[22:23], s[34:35] op_sel_hi:[1,0]
	v_pk_mul_f32 v[14:15], v[20:21], s[34:35] op_sel_hi:[1,0]
	v_pk_fma_f32 v[10:11], v[10:11], v[58:59], v[12:13]
	v_pk_fma_f32 v[8:9], v[8:9], v[56:57], v[14:15]
	flat_store_dwordx4 v[80:81], v[8:11] offset:528
	v_sub_f32_e32 v13, v91, v140
	v_sub_f32_e32 v12, v90, v140
	v_sub_f32_e32 v9, v83, v140
	v_sub_f32_e32 v8, v82, v140
	v_sub_f32_e32 v11, v85, v140
	v_sub_f32_e32 v10, v84, v140
	v_pk_mul_f32 v[10:11], v[140:141], v[10:11] op_sel:[1,0]
	v_pk_mul_f32 v[8:9], v[140:141], v[8:9] op_sel:[1,0]
	v_pk_fma_f32 v[10:11], v[10:11], v[34:35], v[38:39]
	v_pk_fma_f32 v[8:9], v[8:9], v[32:33], v[36:37]
	v_sub_f32_e32 v15, v93, v140
	v_sub_f32_e32 v14, v92, v140
	v_pk_mul_f32 v[14:15], v[140:141], v[14:15] op_sel:[1,0]
	v_pk_mul_f32 v[12:13], v[140:141], v[12:13] op_sel:[1,0]
	v_pk_mul_f32 v[10:11], v[10:11], s[34:35] op_sel_hi:[1,0]
	v_pk_mul_f32 v[8:9], v[8:9], s[34:35] op_sel_hi:[1,0]
	v_pk_fma_f32 v[12:13], v[12:13], v[44:45], v[48:49]
	v_pk_fma_f32 v[14:15], v[14:15], v[46:47], v[50:51]
	v_pk_fma_f32 v[4:5], v[4:5], v[52:53], v[8:9]
	v_pk_fma_f32 v[6:7], v[6:7], v[54:55], v[10:11]
	flat_store_dwordx4 v[72:73], v[4:7] offset:512
	s_nop 1
	v_pk_mul_f32 v[4:5], v[14:15], s[34:35] op_sel_hi:[1,0]
	v_pk_mul_f32 v[6:7], v[12:13], s[34:35] op_sel_hi:[1,0]
	v_pk_fma_f32 v[2:3], v[2:3], v[58:59], v[4:5]
	v_pk_fma_f32 v[0:1], v[0:1], v[56:57], v[6:7]
	flat_store_dwordx4 v[72:73], v[0:3] offset:528
	s_cbranch_vccnz .LBB0_678
	s_andn2_b64 vcc, exec, s[16:17]
	s_cbranch_vccnz .LBB0_677
	s_barrier
	s_branch .LBB0_677

; #define EPIRES_LOAD(q_, buf_) do { const int bj_ = (q_) >> 1, ai_ = (q_) & 1; \
;             _Pragma("unroll") for (int m = 0; m < 4; ++m) { const float* xp = Xin + (size_t)(row0 + ai_ * HALF + m * 16) * D + col0 + bj_ * HALF; xa[buf_][m] = *(const f32x4*)xp; xb[buf_][m] = *(const f32x4*)(xp + 4); } } while (0)
;     __device__ __forceinline__ void operator()(const f32x4 (&acc)[2][2][4][2], const Unit& u, int wr, int wc, int fr, int fq) const {
;         typedef float f32x2_t __attribute__((ext_vector_type(2)));
;         const int row0 = u.pm * BM + wr * 64 + fr, col0 = u.pn * BM + wc * 32 + 8 * fq;
;         const float* gp = gate + (size_t)((u.pm * BM) >> 11) * 6144 + col0;
;         f32x2_t st[2][4];
; #pragma unroll
;         for (int ai = 0; ai < 2; ++ai)
; #pragma unroll
;             for (int m = 0; m < 4; ++m) st[ai][m] = stats ? *(const f32x2_t*)(stats + 2 * (row0 + ai * HALF + m * 16)) : (f32x2_t){0.f, 1.f};
;         f32x4 xa[2][4], xb[2][4];
;     ...
;         EPIRES_LOAD(0, 0);
; #pragma unroll
;         for (int q = 0; q < 4; ++q) { const int bj = q >> 1, ai = q & 1, co = col0 + bj * HALF, cb = q & 1;
;             if (q + 1 < 4) EPIRES_LOAD(q + 1, cb ^ 1);
;             const f32x4 g0 = *(const f32x4*)(gp + bj * HALF), g1 = *(const f32x4*)(gp + bj * HALF + 4);
;             f32x4 w0 = {1.f, 1.f, 1.f, 1.f}, w1 = w0, b0 = {0.f, 0.f, 0.f, 0.f}, b1 = b0;
;             if (stats) { w0 = *(const f32x4*)(lw + co); w1 = *(const f32x4*)(lw + co + 4); b0 = *(const f32x4*)(lb + co); b1 = *(const f32x4*)(lb + co + 4); }
; #pragma unroll
;             for (int m = 0; m < 4; ++m) { float* op = Xout + (size_t)(row0 + ai * HALF + m * 16) * D + co;
;                 f32x4 x0 = xa[cb][m], x1 = xb[cb][m];
;                 if (stats) { x0 = (x0 - st[ai][m].x) * st[ai][m].y * w0 + b0; x1 = (x1 - st[ai][m].x) * st[ai][m].y * w1 + b1; }
;                 *(f32x4*)op = x0 * ALPHA + g0 * acc[ai][bj][m][0]; *(f32x4*)(op + 4) = x1 * ALPHA + g1 * acc[ai][bj][m][1]; } }
.LBB0_1193:
	v_lshl_add_u32 v140, s46, 8, v182
	v_lshl_add_u32 v142, s63, 8, v184
	v_ashrrev_i32_e32 v143, 31, v142
	v_lshlrev_b32_e32 v144, 1, v140
	v_ashrrev_i32_e32 v145, 31, v144
	v_lshlrev_b64 v[168:169], 2, v[142:143]
	v_ashrrev_i32_e32 v141, 31, v140
	v_lshl_add_u64 v[152:153], v[144:145], 2, s[16:17]
	v_lshl_add_u64 v[176:177], s[14:15], 0, v[168:169]
	v_lshlrev_b64 v[178:179], 12, v[140:141]
	s_ashr_i32 s35, s46, 3
	flat_load_dwordx2 v[158:159], v[152:153]
	v_lshl_add_u64 v[164:165], v[176:177], 0, v[178:179]
	s_mul_hi_i32 s37, s35, 0x6000
	s_mulk_i32 s35, 0x6000
	flat_load_dwordx4 v[188:191], v[164:165]
	flat_load_dwordx4 v[192:195], v[164:165] offset:16
	s_add_u32 s48, s55, s35
	s_addc_u32 s49, s56, s37
	v_lshl_add_u64 v[146:147], s[8:9], 0, v[168:169]
	v_lshl_add_u64 v[150:151], s[48:49], 0, v[168:169]
	v_lshl_add_u64 v[148:149], s[6:7], 0, v[168:169]
	flat_load_dwordx4 v[196:199], v[146:147]
	flat_load_dwordx4 v[200:203], v[148:149]
	flat_load_dwordx4 v[204:207], v[148:149] offset:16
	flat_load_dwordx4 v[208:211], v[146:147] offset:16
	flat_load_dwordx4 v[212:215], v[150:151]
	flat_load_dwordx4 v[216:219], v[150:151] offset:16
	v_or_b32_e32 v142, 16, v140
	v_ashrrev_i32_e32 v143, 31, v142
	v_lshlrev_b64 v[248:249], 12, v[142:143]
	flat_load_dwordx2 v[162:163], v[152:153] offset:128
	v_lshl_add_u64 v[170:171], v[176:177], 0, v[248:249]
	flat_load_dwordx4 v[220:223], v[170:171]
	flat_load_dwordx4 v[224:227], v[170:171] offset:16
	v_or_b32_e32 v142, 32, v140
	v_ashrrev_i32_e32 v143, 31, v142
	v_lshlrev_b64 v[250:251], 12, v[142:143]
	v_lshl_add_u64 v[172:173], v[176:177], 0, v[250:251]
	flat_load_dwordx2 v[160:161], v[152:153] offset:256
	flat_load_dwordx4 v[228:231], v[172:173]
	flat_load_dwordx4 v[232:235], v[172:173] offset:16
	flat_load_dwordx2 v[156:157], v[152:153] offset:384
	v_or_b32_e32 v140, 48, v140
	v_add_u32_e32 v154, 0x100, v144
	v_add_u32_e32 v166, 0x120, v144
	v_add_u32_e32 v174, 0x140, v144
	v_add_u32_e32 v144, 0x160, v144
	v_ashrrev_i32_e32 v141, 31, v140
	v_ashrrev_i32_e32 v155, 31, v154
	v_ashrrev_i32_e32 v167, 31, v166
	v_ashrrev_i32_e32 v175, 31, v174
	v_ashrrev_i32_e32 v145, 31, v144
	v_lshlrev_b64 v[252:253], 12, v[140:141]
	v_lshl_add_u64 v[180:181], v[178:179], 0, s[22:23]
	v_lshl_add_u64 v[140:141], s[14:15], 0, v[178:179]
	v_lshl_add_u64 v[142:143], v[154:155], 2, s[16:17]
	v_lshl_add_u64 v[236:237], v[166:167], 2, s[16:17]
	v_lshl_add_u64 v[238:239], v[174:175], 2, s[16:17]
	v_lshl_add_u64 v[240:241], v[144:145], 2, s[16:17]
	v_lshl_add_u64 v[174:175], v[176:177], 0, v[252:253]
	v_lshl_add_u64 v[154:155], v[176:177], 0, v[180:181]
	v_lshl_add_u64 v[166:167], v[140:141], 0, v[168:169]
	flat_load_dwordx2 v[152:153], v[142:143]
	flat_load_dwordx2 v[144:145], v[236:237]
	s_nop 0
	flat_load_dwordx2 v[142:143], v[238:239]
	flat_load_dwordx2 v[140:141], v[240:241]
	s_nop 0
	flat_load_dwordx4 v[236:239], v[174:175]
	flat_load_dwordx4 v[240:243], v[174:175] offset:16
	flat_load_dwordx4 v[244:247], v[154:155]
	s_andn2_b64 vcc, exec, s[4:5]
	s_mov_b64 s[4:5], -1
	s_waitcnt vmcnt(0) lgkmcnt(0)
	v_sub_f32_e32 v191, v191, v158
	v_sub_f32_e32 v190, v190, v158
	v_sub_f32_e32 v189, v189, v158
	v_sub_f32_e32 v188, v188, v158
	v_pk_mul_f32 v[188:189], v[158:159], v[188:189] op_sel:[1,0]
	v_pk_mul_f32 v[190:191], v[158:159], v[190:191] op_sel:[1,0]
	v_sub_f32_e32 v195, v195, v158
	v_sub_f32_e32 v194, v194, v158
	v_sub_f32_e32 v193, v193, v158
	v_sub_f32_e32 v192, v192, v158
	v_pk_fma_f32 v[190:191], v[190:191], v[202:203], v[198:199]
	v_pk_fma_f32 v[188:189], v[188:189], v[200:201], v[196:197]
	v_pk_mul_f32 v[192:193], v[158:159], v[192:193] op_sel:[1,0]
	v_pk_mul_f32 v[194:195], v[158:159], v[194:195] op_sel:[1,0]
	v_pk_mul_f32 v[188:189], v[188:189], s[30:31] op_sel_hi:[1,0]
	v_pk_mul_f32 v[190:191], v[190:191], s[30:31] op_sel_hi:[1,0]
	v_pk_fma_f32 v[194:195], v[194:195], v[206:207], v[210:211]
	v_pk_fma_f32 v[192:193], v[192:193], v[204:205], v[208:209]
	v_pk_fma_f32 v[126:127], v[126:127], v[214:215], v[190:191]
	v_pk_fma_f32 v[124:125], v[124:125], v[212:213], v[188:189]
	flat_store_dwordx4 v[166:167], v[124:127]
	v_sub_f32_e32 v189, v225, v162
	v_sub_f32_e32 v188, v224, v162
	v_pk_mul_f32 v[124:125], v[192:193], s[30:31] op_sel_hi:[1,0]
	v_pk_mul_f32 v[126:127], v[194:195], s[30:31] op_sel_hi:[1,0]
	v_pk_fma_f32 v[120:121], v[120:121], v[216:217], v[124:125]
	v_pk_fma_f32 v[122:123], v[122:123], v[218:219], v[126:127]
	flat_store_dwordx4 v[166:167], v[120:123] offset:16
	v_sub_f32_e32 v125, v221, v162
	v_sub_f32_e32 v124, v220, v162
	v_sub_f32_e32 v123, v223, v162
	v_sub_f32_e32 v122, v222, v162
	v_pk_mul_f32 v[124:125], v[162:163], v[124:125] op_sel:[1,0]
	v_pk_mul_f32 v[122:123], v[162:163], v[122:123] op_sel:[1,0]
	v_pk_fma_f32 v[124:125], v[124:125], v[200:201], v[196:197]
	v_pk_fma_f32 v[122:123], v[122:123], v[202:203], v[198:199]
	v_sub_f32_e32 v127, v227, v162
	v_sub_f32_e32 v126, v226, v162
	v_lshl_add_u64 v[120:121], s[14:15], 0, v[248:249]
	v_pk_mul_f32 v[188:189], v[162:163], v[188:189] op_sel:[1,0]
	v_pk_mul_f32 v[126:127], v[162:163], v[126:127] op_sel:[1,0]
	v_pk_mul_f32 v[124:125], v[124:125], s[30:31] op_sel_hi:[1,0]
	v_pk_mul_f32 v[122:123], v[122:123], s[30:31] op_sel_hi:[1,0]
	v_lshl_add_u64 v[120:121], v[120:121], 0, v[168:169]
	v_pk_fma_f32 v[126:127], v[126:127], v[206:207], v[210:211]
	v_pk_fma_f32 v[188:189], v[188:189], v[204:205], v[208:209]
	v_pk_fma_f32 v[118:119], v[118:119], v[214:215], v[122:123]
	v_pk_fma_f32 v[116:117], v[116:117], v[212:213], v[124:125]
	flat_store_dwordx4 v[120:121], v[116:119]
	v_sub_f32_e32 v123, v233, v160
	v_sub_f32_e32 v122, v232, v160
; #define EPIRES_LOAD(q_, buf_) do { const int bj_ = (q_) >> 1, ai_ = (q_) & 1; \
;             _Pragma("unroll") for (int m = 0; m < 4; ++m) { const float* xp = Xin + (size_t)(row0 + ai_ * HALF + m * 16) * D + col0 + bj_ * HALF; xa[buf_][m] = *(const f32x4*)xp; xb[buf_][m] = *(const f32x4*)(xp + 4); } } while (0)
;     __device__ __forceinline__ void operator()(const f32x4 (&acc)[2][2][4][2], const Unit& u, int wr, int wc, int fr, int fq) const {
;     ...
;         EPIRES_LOAD(0, 0);
; #pragma unroll
;         for (int q = 0; q < 4; ++q) { const int bj = q >> 1, ai = q & 1, co = col0 + bj * HALF, cb = q & 1;
;             if (q + 1 < 4) EPIRES_LOAD(q + 1, cb ^ 1);
;             const f32x4 g0 = *(const f32x4*)(gp + bj * HALF), g1 = *(const f32x4*)(gp + bj * HALF + 4);
;             f32x4 w0 = {1.f, 1.f, 1.f, 1.f}, w1 = w0, b0 = {0.f, 0.f, 0.f, 0.f}, b1 = b0;
;             if (stats) { w0 = *(const f32x4*)(lw + co); w1 = *(const f32x4*)(lw + co + 4); b0 = *(const f32x4*)(lb + co); b1 = *(const f32x4*)(lb + co + 4); }
; #pragma unroll
;             for (int m = 0; m < 4; ++m) { float* op = Xout + (size_t)(row0 + ai * HALF + m * 16) * D + co;
;                 f32x4 x0 = xa[cb][m], x1 = xb[cb][m];
;                 if (stats) { x0 = (x0 - st[ai][m].x) * st[ai][m].y * w0 + b0; x1 = (x1 - st[ai][m].x) * st[ai][m].y * w1 + b1; }
;                 *(f32x4*)op = x0 * ALPHA + g0 * acc[ai][bj][m][0]; *(f32x4*)(op + 4) = x1 * ALPHA + g1 * acc[ai][bj][m][1]; } }
	v_pk_mul_f32 v[116:117], v[188:189], s[30:31] op_sel_hi:[1,0]
	v_pk_mul_f32 v[118:119], v[126:127], s[30:31] op_sel_hi:[1,0]
	v_pk_fma_f32 v[112:113], v[112:113], v[216:217], v[116:117]
	v_pk_fma_f32 v[114:115], v[114:115], v[218:219], v[118:119]
	flat_store_dwordx4 v[120:121], v[112:115] offset:16
	v_sub_f32_e32 v117, v229, v160
	v_sub_f32_e32 v116, v228, v160
	v_sub_f32_e32 v115, v231, v160
	v_sub_f32_e32 v114, v230, v160
	v_pk_mul_f32 v[116:117], v[160:161], v[116:117] op_sel:[1,0]
	v_pk_mul_f32 v[114:115], v[160:161], v[114:115] op_sel:[1,0]
	v_pk_fma_f32 v[116:117], v[116:117], v[200:201], v[196:197]
	v_pk_fma_f32 v[114:115], v[114:115], v[202:203], v[198:199]
	v_sub_f32_e32 v119, v235, v160
	v_sub_f32_e32 v118, v234, v160
	v_lshl_add_u64 v[112:113], s[14:15], 0, v[250:251]
	v_pk_mul_f32 v[122:123], v[160:161], v[122:123] op_sel:[1,0]
	v_pk_mul_f32 v[118:119], v[160:161], v[118:119] op_sel:[1,0]
	v_pk_mul_f32 v[116:117], v[116:117], s[30:31] op_sel_hi:[1,0]
	v_pk_mul_f32 v[114:115], v[114:115], s[30:31] op_sel_hi:[1,0]
	v_lshl_add_u64 v[112:113], v[112:113], 0, v[168:169]
	v_pk_fma_f32 v[118:119], v[118:119], v[206:207], v[210:211]
	v_pk_fma_f32 v[122:123], v[122:123], v[204:205], v[208:209]
	v_pk_fma_f32 v[110:111], v[110:111], v[214:215], v[114:115]
	v_pk_fma_f32 v[108:109], v[108:109], v[212:213], v[116:117]
	flat_store_dwordx4 v[112:113], v[108:111]
	v_sub_f32_e32 v115, v241, v156
	v_sub_f32_e32 v114, v240, v156
	v_pk_mul_f32 v[108:109], v[122:123], s[30:31] op_sel_hi:[1,0]
	v_pk_mul_f32 v[110:111], v[118:119], s[30:31] op_sel_hi:[1,0]
	v_pk_fma_f32 v[104:105], v[104:105], v[216:217], v[108:109]
	v_pk_fma_f32 v[106:107], v[106:107], v[218:219], v[110:111]
	flat_store_dwordx4 v[112:113], v[104:107] offset:16
	v_sub_f32_e32 v109, v237, v156
	v_sub_f32_e32 v108, v236, v156
	v_sub_f32_e32 v107, v239, v156
	v_sub_f32_e32 v106, v238, v156
	v_pk_mul_f32 v[108:109], v[156:157], v[108:109] op_sel:[1,0]
	v_pk_mul_f32 v[106:107], v[156:157], v[106:107] op_sel:[1,0]
	v_pk_fma_f32 v[108:109], v[108:109], v[200:201], v[196:197]
	v_pk_fma_f32 v[106:107], v[106:107], v[202:203], v[198:199]
	v_sub_f32_e32 v111, v243, v156
	v_sub_f32_e32 v110, v242, v156
	v_lshl_add_u64 v[104:105], s[14:15], 0, v[252:253]
	v_pk_mul_f32 v[114:115], v[156:157], v[114:115] op_sel:[1,0]
	v_pk_mul_f32 v[110:111], v[156:157], v[110:111] op_sel:[1,0]
	v_pk_mul_f32 v[108:109], v[108:109], s[30:31] op_sel_hi:[1,0]
	v_pk_mul_f32 v[106:107], v[106:107], s[30:31] op_sel_hi:[1,0]
	v_lshl_add_u64 v[104:105], v[104:105], 0, v[168:169]
	v_pk_fma_f32 v[110:111], v[110:111], v[206:207], v[210:211]
	v_pk_fma_f32 v[114:115], v[114:115], v[204:205], v[208:209]
	v_pk_fma_f32 v[102:103], v[102:103], v[214:215], v[106:107]
	v_pk_fma_f32 v[100:101], v[100:101], v[212:213], v[108:109]
	flat_store_dwordx4 v[104:105], v[100:103]
	v_lshl_add_u64 v[118:119], v[178:179], 0, s[26:27]
	v_lshl_add_u64 v[126:127], v[178:179], 0, s[28:29]
	v_pk_mul_f32 v[100:101], v[114:115], s[30:31] op_sel_hi:[1,0]
	v_pk_mul_f32 v[102:103], v[110:111], s[30:31] op_sel_hi:[1,0]
	v_pk_fma_f32 v[96:97], v[96:97], v[216:217], v[100:101]
	v_pk_fma_f32 v[98:99], v[98:99], v[218:219], v[102:103]
	flat_store_dwordx4 v[104:105], v[96:99] offset:16
	flat_load_dwordx4 v[106:109], v[148:149]
	flat_load_dwordx4 v[114:117], v[146:147]
	flat_load_dwordx4 v[122:125], v[154:155] offset:16
	flat_load_dwordx4 v[188:191], v[148:149] offset:16
	flat_load_dwordx4 v[192:195], v[146:147] offset:16
	flat_load_dwordx4 v[196:199], v[150:151]
	flat_load_dwordx4 v[200:203], v[150:151] offset:16
	v_lshl_add_u64 v[110:111], v[178:179], 0, s[24:25]
	v_lshl_add_u64 v[98:99], v[176:177], 0, v[110:111]
	flat_load_dwordx4 v[204:207], v[98:99]
	flat_load_dwordx4 v[208:211], v[98:99] offset:16
	v_lshl_add_u64 v[100:101], v[176:177], 0, v[118:119]
	flat_load_dwordx4 v[212:215], v[100:101]
	flat_load_dwordx4 v[216:219], v[100:101] offset:16
	v_lshl_add_u64 v[102:103], v[176:177], 0, v[126:127]
	flat_load_dwordx4 v[176:179], v[102:103]
	flat_load_dwordx4 v[220:223], v[102:103] offset:16
	flat_load_dwordx4 v[224:227], v[164:165] offset:512
	v_lshl_add_u64 v[96:97], s[14:15], 0, v[180:181]
	v_sub_f32_e32 v181, v245, v152
	v_sub_f32_e32 v180, v244, v152
	v_sub_f32_e32 v229, v247, v152
	v_sub_f32_e32 v228, v246, v152
	v_pk_mul_f32 v[228:229], v[152:153], v[228:229] op_sel:[1,0]
	v_pk_mul_f32 v[180:181], v[152:153], v[180:181] op_sel:[1,0]
	v_lshl_add_u64 v[96:97], v[96:97], 0, v[168:169]
	s_waitcnt vmcnt(0) lgkmcnt(0)
; #define EPIRES_LOAD(q_, buf_) do { const int bj_ = (q_) >> 1, ai_ = (q_) & 1; \
;             _Pragma("unroll") for (int m = 0; m < 4; ++m) { const float* xp = Xin + (size_t)(row0 + ai_ * HALF + m * 16) * D + col0 + bj_ * HALF; xa[buf_][m] = *(const f32x4*)xp; xb[buf_][m] = *(const f32x4*)(xp + 4); } } while (0)
;     __device__ __forceinline__ void operator()(const f32x4 (&acc)[2][2][4][2], const Unit& u, int wr, int wc, int fr, int fq) const {
;     ...
;         EPIRES_LOAD(0, 0);
; #pragma unroll
;         for (int q = 0; q < 4; ++q) { const int bj = q >> 1, ai = q & 1, co = col0 + bj * HALF, cb = q & 1;
;             if (q + 1 < 4) EPIRES_LOAD(q + 1, cb ^ 1);
;             const f32x4 g0 = *(const f32x4*)(gp + bj * HALF), g1 = *(const f32x4*)(gp + bj * HALF + 4);
;             f32x4 w0 = {1.f, 1.f, 1.f, 1.f}, w1 = w0, b0 = {0.f, 0.f, 0.f, 0.f}, b1 = b0;
;             if (stats) { w0 = *(const f32x4*)(lw + co); w1 = *(const f32x4*)(lw + co + 4); b0 = *(const f32x4*)(lb + co); b1 = *(const f32x4*)(lb + co + 4); }
; #pragma unroll
;             for (int m = 0; m < 4; ++m) { float* op = Xout + (size_t)(row0 + ai * HALF + m * 16) * D + co;
;                 f32x4 x0 = xa[cb][m], x1 = xb[cb][m];
;                 if (stats) { x0 = (x0 - st[ai][m].x) * st[ai][m].y * w0 + b0; x1 = (x1 - st[ai][m].x) * st[ai][m].y * w1 + b1; }
;                 *(f32x4*)op = x0 * ALPHA + g0 * acc[ai][bj][m][0]; *(f32x4*)(op + 4) = x1 * ALPHA + g1 * acc[ai][bj][m][1]; } }
	v_pk_fma_f32 v[180:181], v[180:181], v[106:107], v[114:115]
	v_pk_fma_f32 v[228:229], v[228:229], v[108:109], v[116:117]
	v_sub_f32_e32 v123, v123, v152
	v_sub_f32_e32 v122, v122, v152
	v_sub_f32_e32 v125, v125, v152
	v_sub_f32_e32 v124, v124, v152
	v_pk_mul_f32 v[124:125], v[152:153], v[124:125] op_sel:[1,0]
	v_pk_mul_f32 v[122:123], v[152:153], v[122:123] op_sel:[1,0]
	v_pk_mul_f32 v[228:229], v[228:229], s[30:31] op_sel_hi:[1,0]
	v_pk_mul_f32 v[180:181], v[180:181], s[30:31] op_sel_hi:[1,0]
	v_pk_fma_f32 v[122:123], v[122:123], v[188:189], v[192:193]
	v_pk_fma_f32 v[124:125], v[124:125], v[190:191], v[194:195]
	v_pk_fma_f32 v[92:93], v[92:93], v[196:197], v[180:181]
	v_pk_fma_f32 v[94:95], v[94:95], v[198:199], v[228:229]
	flat_store_dwordx4 v[96:97], v[92:95]
	s_nop 1
	v_pk_mul_f32 v[92:93], v[124:125], s[30:31] op_sel_hi:[1,0]
	v_pk_mul_f32 v[94:95], v[122:123], s[30:31] op_sel_hi:[1,0]
	v_pk_fma_f32 v[90:91], v[90:91], v[202:203], v[92:93]
	v_pk_fma_f32 v[88:89], v[88:89], v[200:201], v[94:95]
	flat_store_dwordx4 v[96:97], v[88:91] offset:16
	v_sub_f32_e32 v93, v207, v144
	v_sub_f32_e32 v92, v206, v144
	v_sub_f32_e32 v91, v205, v144
	v_sub_f32_e32 v90, v204, v144
	v_pk_mul_f32 v[92:93], v[144:145], v[92:93] op_sel:[1,0]
	v_pk_mul_f32 v[90:91], v[144:145], v[90:91] op_sel:[1,0]
	v_lshl_add_u64 v[88:89], s[14:15], 0, v[110:111]
	v_pk_fma_f32 v[90:91], v[90:91], v[106:107], v[114:115]
	v_pk_fma_f32 v[92:93], v[92:93], v[108:109], v[116:117]
	v_sub_f32_e32 v95, v209, v144
	v_sub_f32_e32 v94, v208, v144
	v_sub_f32_e32 v111, v211, v144
	v_sub_f32_e32 v110, v210, v144
	v_pk_mul_f32 v[110:111], v[144:145], v[110:111] op_sel:[1,0]
	v_pk_mul_f32 v[94:95], v[144:145], v[94:95] op_sel:[1,0]
	v_pk_mul_f32 v[92:93], v[92:93], s[30:31] op_sel_hi:[1,0]
	v_pk_mul_f32 v[90:91], v[90:91], s[30:31] op_sel_hi:[1,0]
	v_lshl_add_u64 v[88:89], v[88:89], 0, v[168:169]
	v_pk_fma_f32 v[94:95], v[94:95], v[188:189], v[192:193]
	v_pk_fma_f32 v[110:111], v[110:111], v[190:191], v[194:195]
	v_pk_fma_f32 v[84:85], v[84:85], v[196:197], v[90:91]
	v_pk_fma_f32 v[86:87], v[86:87], v[198:199], v[92:93]
	flat_store_dwordx4 v[88:89], v[84:87]
	v_sub_f32_e32 v91, v219, v142
	v_sub_f32_e32 v90, v218, v142
	v_pk_mul_f32 v[84:85], v[110:111], s[30:31] op_sel_hi:[1,0]
	v_pk_mul_f32 v[86:87], v[94:95], s[30:31] op_sel_hi:[1,0]
	v_pk_fma_f32 v[82:83], v[82:83], v[202:203], v[84:85]
	v_pk_fma_f32 v[80:81], v[80:81], v[200:201], v[86:87]
	flat_store_dwordx4 v[88:89], v[80:83] offset:16
	v_sub_f32_e32 v85, v215, v142
	v_sub_f32_e32 v84, v214, v142
	v_sub_f32_e32 v83, v213, v142
	v_sub_f32_e32 v82, v212, v142
	v_pk_mul_f32 v[84:85], v[142:143], v[84:85] op_sel:[1,0]
	v_pk_mul_f32 v[82:83], v[142:143], v[82:83] op_sel:[1,0]
	v_pk_fma_f32 v[84:85], v[84:85], v[108:109], v[116:117]
	v_pk_fma_f32 v[82:83], v[82:83], v[106:107], v[114:115]
	v_sub_f32_e32 v87, v217, v142
	v_sub_f32_e32 v86, v216, v142
	v_lshl_add_u64 v[80:81], s[14:15], 0, v[118:119]
	v_pk_mul_f32 v[90:91], v[142:143], v[90:91] op_sel:[1,0]
	v_pk_mul_f32 v[86:87], v[142:143], v[86:87] op_sel:[1,0]
	v_pk_mul_f32 v[84:85], v[84:85], s[30:31] op_sel_hi:[1,0]
	v_pk_mul_f32 v[82:83], v[82:83], s[30:31] op_sel_hi:[1,0]
	v_lshl_add_u64 v[80:81], v[80:81], 0, v[168:169]
	v_pk_fma_f32 v[86:87], v[86:87], v[188:189], v[192:193]
	v_pk_fma_f32 v[90:91], v[90:91], v[190:191], v[194:195]
	v_pk_fma_f32 v[76:77], v[76:77], v[196:197], v[82:83]
	v_pk_fma_f32 v[78:79], v[78:79], v[198:199], v[84:85]
	flat_store_dwordx4 v[80:81], v[76:79]
	v_sub_f32_e32 v83, v223, v140
	v_sub_f32_e32 v82, v222, v140
	v_pk_mul_f32 v[76:77], v[90:91], s[30:31] op_sel_hi:[1,0]
	v_pk_mul_f32 v[78:79], v[86:87], s[30:31] op_sel_hi:[1,0]
	v_pk_fma_f32 v[74:75], v[74:75], v[202:203], v[76:77]
	v_pk_fma_f32 v[72:73], v[72:73], v[200:201], v[78:79]
	flat_store_dwordx4 v[80:81], v[72:75] offset:16
	v_sub_f32_e32 v77, v179, v140
	v_sub_f32_e32 v76, v178, v140
	v_sub_f32_e32 v75, v177, v140
	v_sub_f32_e32 v74, v176, v140
	v_pk_mul_f32 v[76:77], v[140:141], v[76:77] op_sel:[1,0]
	v_pk_mul_f32 v[74:75], v[140:141], v[74:75] op_sel:[1,0]
	v_pk_fma_f32 v[76:77], v[76:77], v[108:109], v[116:117]
	v_pk_fma_f32 v[74:75], v[74:75], v[106:107], v[114:115]
	v_sub_f32_e32 v79, v221, v140
	v_sub_f32_e32 v78, v220, v140
	v_lshl_add_u64 v[72:73], s[14:15], 0, v[126:127]
	v_pk_mul_f32 v[82:83], v[140:141], v[82:83] op_sel:[1,0]
	v_pk_mul_f32 v[78:79], v[140:141], v[78:79] op_sel:[1,0]
	v_pk_mul_f32 v[76:77], v[76:77], s[30:31] op_sel_hi:[1,0]
	v_pk_mul_f32 v[74:75], v[74:75], s[30:31] op_sel_hi:[1,0]
	v_lshl_add_u64 v[72:73], v[72:73], 0, v[168:169]
	v_pk_fma_f32 v[78:79], v[78:79], v[188:189], v[192:193]
	v_pk_fma_f32 v[82:83], v[82:83], v[190:191], v[194:195]
	v_pk_fma_f32 v[68:69], v[68:69], v[196:197], v[74:75]
	v_pk_fma_f32 v[70:71], v[70:71], v[198:199], v[76:77]
	flat_store_dwordx4 v[72:73], v[68:71]
	v_sub_f32_e32 v87, v227, v158
	v_sub_f32_e32 v86, v226, v158
	v_pk_mul_f32 v[68:69], v[82:83], s[30:31] op_sel_hi:[1,0]
	v_pk_mul_f32 v[70:71], v[78:79], s[30:31] op_sel_hi:[1,0]
	v_pk_fma_f32 v[66:67], v[66:67], v[202:203], v[68:69]
	v_pk_fma_f32 v[64:65], v[64:65], v[200:201], v[70:71]
	flat_store_dwordx4 v[72:73], v[64:67] offset:16
	flat_load_dwordx4 v[200:203], v[154:155] offset:512
	flat_load_dwordx4 v[204:207], v[154:155] offset:528
	flat_load_dwordx4 v[208:211], v[98:99] offset:512
	flat_load_dwordx4 v[212:215], v[98:99] offset:528
	flat_load_dwordx4 v[216:219], v[100:101] offset:512
	flat_load_dwordx4 v[220:223], v[100:101] offset:528
	flat_load_dwordx4 v[226:229], v[102:103] offset:512
	flat_load_dwordx4 v[230:233], v[102:103] offset:528
	flat_load_dwordx4 v[64:67], v[148:149] offset:512
	s_nop 0
	flat_load_dwordx4 v[68:71], v[146:147] offset:512
	flat_load_dwordx4 v[74:77], v[164:165] offset:528
	flat_load_dwordx4 v[82:85], v[148:149] offset:528
	flat_load_dwordx4 v[90:93], v[146:147] offset:528
	flat_load_dwordx4 v[106:109], v[150:151] offset:512
	flat_load_dwordx4 v[114:117], v[150:151] offset:528
	flat_load_dwordx4 v[122:125], v[170:171] offset:512
	s_nop 0
	flat_load_dwordx4 v[168:171], v[170:171] offset:528
	s_nop 0
	flat_load_dwordx4 v[176:179], v[172:173] offset:512
	flat_load_dwordx4 v[188:191], v[172:173] offset:528
	flat_load_dwordx4 v[192:195], v[174:175] offset:512
	s_nop 0
	flat_load_dwordx4 v[172:175], v[174:175] offset:528
	s_nop 0
	v_sub_f32_e32 v79, v225, v158
	v_sub_f32_e32 v78, v224, v158
	v_pk_mul_f32 v[86:87], v[158:159], v[86:87] op_sel:[1,0]
	v_pk_mul_f32 v[78:79], v[158:159], v[78:79] op_sel:[1,0]
	s_waitcnt vmcnt(0) lgkmcnt(0)
; #define EPIRES_LOAD(q_, buf_) do { const int bj_ = (q_) >> 1, ai_ = (q_) & 1; \
;             _Pragma("unroll") for (int m = 0; m < 4; ++m) { const float* xp = Xin + (size_t)(row0 + ai_ * HALF + m * 16) * D + col0 + bj_ * HALF; xa[buf_][m] = *(const f32x4*)xp; xb[buf_][m] = *(const f32x4*)(xp + 4); } } while (0)
;     __device__ __forceinline__ void operator()(const f32x4 (&acc)[2][2][4][2], const Unit& u, int wr, int wc, int fr, int fq) const {
;     ...
;         EPIRES_LOAD(0, 0);
; #pragma unroll
;         for (int q = 0; q < 4; ++q) { const int bj = q >> 1, ai = q & 1, co = col0 + bj * HALF, cb = q & 1;
;             if (q + 1 < 4) EPIRES_LOAD(q + 1, cb ^ 1);
;             const f32x4 g0 = *(const f32x4*)(gp + bj * HALF), g1 = *(const f32x4*)(gp + bj * HALF + 4);
;             f32x4 w0 = {1.f, 1.f, 1.f, 1.f}, w1 = w0, b0 = {0.f, 0.f, 0.f, 0.f}, b1 = b0;
;             if (stats) { w0 = *(const f32x4*)(lw + co); w1 = *(const f32x4*)(lw + co + 4); b0 = *(const f32x4*)(lb + co); b1 = *(const f32x4*)(lb + co + 4); }
; #pragma unroll
;             for (int m = 0; m < 4; ++m) { float* op = Xout + (size_t)(row0 + ai * HALF + m * 16) * D + co;
;                 f32x4 x0 = xa[cb][m], x1 = xb[cb][m];
;                 if (stats) { x0 = (x0 - st[ai][m].x) * st[ai][m].y * w0 + b0; x1 = (x1 - st[ai][m].x) * st[ai][m].y * w1 + b1; }
;                 *(f32x4*)op = x0 * ALPHA + g0 * acc[ai][bj][m][0]; *(f32x4*)(op + 4) = x1 * ALPHA + g1 * acc[ai][bj][m][1]; } }
	v_mov_b32_e32 v196, v200
	v_mov_b32_e32 v197, v201
	v_mov_b32_e32 v198, v202
	v_mov_b32_e32 v199, v203
	v_pk_fma_f32 v[86:87], v[86:87], v[66:67], v[70:71]
	v_pk_fma_f32 v[78:79], v[78:79], v[64:65], v[68:69]
	v_sub_f32_e32 v75, v75, v158
	v_sub_f32_e32 v74, v74, v158
	v_sub_f32_e32 v77, v77, v158
	v_sub_f32_e32 v76, v76, v158
	v_pk_mul_f32 v[76:77], v[158:159], v[76:77] op_sel:[1,0]
	v_pk_mul_f32 v[74:75], v[158:159], v[74:75] op_sel:[1,0]
	v_pk_mul_f32 v[86:87], v[86:87], s[30:31] op_sel_hi:[1,0]
	v_pk_mul_f32 v[78:79], v[78:79], s[30:31] op_sel_hi:[1,0]
	v_pk_fma_f32 v[74:75], v[74:75], v[82:83], v[90:91]
	v_pk_fma_f32 v[76:77], v[76:77], v[84:85], v[92:93]
	v_pk_fma_f32 v[60:61], v[60:61], v[106:107], v[78:79]
	v_pk_fma_f32 v[62:63], v[62:63], v[108:109], v[86:87]
	flat_store_dwordx4 v[166:167], v[60:63] offset:512
	v_sub_f32_e32 v79, v197, v152
	v_sub_f32_e32 v78, v196, v152
	v_pk_mul_f32 v[60:61], v[76:77], s[30:31] op_sel_hi:[1,0]
	v_pk_mul_f32 v[62:63], v[74:75], s[30:31] op_sel_hi:[1,0]
	v_pk_fma_f32 v[58:59], v[58:59], v[116:117], v[60:61]
	v_pk_fma_f32 v[56:57], v[56:57], v[114:115], v[62:63]
	flat_store_dwordx4 v[166:167], v[56:59] offset:528
	v_sub_f32_e32 v61, v169, v162
	v_sub_f32_e32 v60, v168, v162
	v_sub_f32_e32 v57, v123, v162
	v_sub_f32_e32 v56, v122, v162
	v_sub_f32_e32 v59, v125, v162
	v_sub_f32_e32 v58, v124, v162
	v_pk_mul_f32 v[58:59], v[162:163], v[58:59] op_sel:[1,0]
	v_pk_mul_f32 v[56:57], v[162:163], v[56:57] op_sel:[1,0]
	v_pk_fma_f32 v[58:59], v[58:59], v[66:67], v[70:71]
	v_pk_fma_f32 v[56:57], v[56:57], v[64:65], v[68:69]
	v_sub_f32_e32 v63, v171, v162
	v_sub_f32_e32 v62, v170, v162
	v_pk_mul_f32 v[62:63], v[162:163], v[62:63] op_sel:[1,0]
	v_pk_mul_f32 v[60:61], v[162:163], v[60:61] op_sel:[1,0]
	v_pk_mul_f32 v[58:59], v[58:59], s[30:31] op_sel_hi:[1,0]
	v_pk_mul_f32 v[56:57], v[56:57], s[30:31] op_sel_hi:[1,0]
	v_pk_fma_f32 v[60:61], v[60:61], v[82:83], v[90:91]
	v_pk_fma_f32 v[62:63], v[62:63], v[84:85], v[92:93]
	v_pk_fma_f32 v[52:53], v[52:53], v[106:107], v[56:57]
	v_pk_fma_f32 v[54:55], v[54:55], v[108:109], v[58:59]
	flat_store_dwordx4 v[120:121], v[52:55] offset:512
	v_sub_f32_e32 v87, v199, v152
	v_sub_f32_e32 v86, v198, v152
	v_pk_mul_f32 v[52:53], v[62:63], s[30:31] op_sel_hi:[1,0]
	v_pk_mul_f32 v[54:55], v[60:61], s[30:31] op_sel_hi:[1,0]
	v_pk_fma_f32 v[50:51], v[50:51], v[116:117], v[52:53]
	v_pk_fma_f32 v[48:49], v[48:49], v[114:115], v[54:55]
	flat_store_dwordx4 v[120:121], v[48:51] offset:528
	v_sub_f32_e32 v53, v189, v160
	v_sub_f32_e32 v52, v188, v160
	v_sub_f32_e32 v49, v177, v160
	v_sub_f32_e32 v48, v176, v160
	v_sub_f32_e32 v51, v179, v160
	v_sub_f32_e32 v50, v178, v160
	v_pk_mul_f32 v[50:51], v[160:161], v[50:51] op_sel:[1,0]
	v_pk_mul_f32 v[48:49], v[160:161], v[48:49] op_sel:[1,0]
	v_pk_fma_f32 v[50:51], v[50:51], v[66:67], v[70:71]
	v_pk_fma_f32 v[48:49], v[48:49], v[64:65], v[68:69]
	v_sub_f32_e32 v55, v191, v160
	v_sub_f32_e32 v54, v190, v160
	v_pk_mul_f32 v[54:55], v[160:161], v[54:55] op_sel:[1,0]
	v_pk_mul_f32 v[52:53], v[160:161], v[52:53] op_sel:[1,0]
	v_pk_mul_f32 v[50:51], v[50:51], s[30:31] op_sel_hi:[1,0]
	v_pk_mul_f32 v[48:49], v[48:49], s[30:31] op_sel_hi:[1,0]
	v_pk_fma_f32 v[52:53], v[52:53], v[82:83], v[90:91]
	v_pk_fma_f32 v[54:55], v[54:55], v[84:85], v[92:93]
	v_pk_fma_f32 v[44:45], v[44:45], v[106:107], v[48:49]
	v_pk_fma_f32 v[46:47], v[46:47], v[108:109], v[50:51]
	flat_store_dwordx4 v[112:113], v[44:47] offset:512
	v_pk_mul_f32 v[86:87], v[152:153], v[86:87] op_sel:[1,0]
	v_pk_mul_f32 v[78:79], v[152:153], v[78:79] op_sel:[1,0]
	v_pk_mul_f32 v[44:45], v[54:55], s[30:31] op_sel_hi:[1,0]
	v_pk_mul_f32 v[46:47], v[52:53], s[30:31] op_sel_hi:[1,0]
	v_pk_fma_f32 v[42:43], v[42:43], v[116:117], v[44:45]
	v_pk_fma_f32 v[40:41], v[40:41], v[114:115], v[46:47]
	flat_store_dwordx4 v[112:113], v[40:43] offset:528
	v_sub_f32_e32 v45, v173, v156
	v_sub_f32_e32 v44, v172, v156
	v_sub_f32_e32 v41, v193, v156
	v_sub_f32_e32 v40, v192, v156
	v_sub_f32_e32 v43, v195, v156
	v_sub_f32_e32 v42, v194, v156
	v_pk_mul_f32 v[42:43], v[156:157], v[42:43] op_sel:[1,0]
	v_pk_mul_f32 v[40:41], v[156:157], v[40:41] op_sel:[1,0]
	v_pk_fma_f32 v[42:43], v[42:43], v[66:67], v[70:71]
	v_pk_fma_f32 v[40:41], v[40:41], v[64:65], v[68:69]
	v_sub_f32_e32 v47, v175, v156
	v_sub_f32_e32 v46, v174, v156
	v_pk_mul_f32 v[46:47], v[156:157], v[46:47] op_sel:[1,0]
	v_pk_mul_f32 v[44:45], v[156:157], v[44:45] op_sel:[1,0]
	v_pk_mul_f32 v[42:43], v[42:43], s[30:31] op_sel_hi:[1,0]
	v_pk_mul_f32 v[40:41], v[40:41], s[30:31] op_sel_hi:[1,0]
	v_pk_fma_f32 v[44:45], v[44:45], v[82:83], v[90:91]
	v_pk_fma_f32 v[46:47], v[46:47], v[84:85], v[92:93]
	v_pk_fma_f32 v[36:37], v[36:37], v[106:107], v[40:41]
	v_pk_fma_f32 v[38:39], v[38:39], v[108:109], v[42:43]
	flat_store_dwordx4 v[104:105], v[36:39] offset:512
	s_nop 1
	v_pk_mul_f32 v[36:37], v[46:47], s[30:31] op_sel_hi:[1,0]
	v_pk_mul_f32 v[38:39], v[44:45], s[30:31] op_sel_hi:[1,0]
	v_pk_fma_f32 v[34:35], v[34:35], v[116:117], v[36:37]
	v_pk_fma_f32 v[32:33], v[32:33], v[114:115], v[38:39]
	flat_store_dwordx4 v[104:105], v[32:35] offset:528
	flat_load_dwordx4 v[32:35], v[148:149] offset:512
	s_nop 0
	flat_load_dwordx4 v[36:39], v[146:147] offset:512
	flat_load_dwordx4 v[44:47], v[148:149] offset:528
	flat_load_dwordx4 v[48:51], v[146:147] offset:528
	flat_load_dwordx4 v[52:55], v[150:151] offset:512
	flat_load_dwordx4 v[56:59], v[150:151] offset:528
	s_waitcnt vmcnt(0) lgkmcnt(0)
; #define EPIRES_LOAD(q_, buf_) do { const int bj_ = (q_) >> 1, ai_ = (q_) & 1; \
;             _Pragma("unroll") for (int m = 0; m < 4; ++m) { const float* xp = Xin + (size_t)(row0 + ai_ * HALF + m * 16) * D + col0 + bj_ * HALF; xa[buf_][m] = *(const f32x4*)xp; xb[buf_][m] = *(const f32x4*)(xp + 4); } } while (0)
;     __device__ __forceinline__ void operator()(const f32x4 (&acc)[2][2][4][2], const Unit& u, int wr, int wc, int fr, int fq) const {
;     ...
;         EPIRES_LOAD(0, 0);
; #pragma unroll
;         for (int q = 0; q < 4; ++q) { const int bj = q >> 1, ai = q & 1, co = col0 + bj * HALF, cb = q & 1;
;             if (q + 1 < 4) EPIRES_LOAD(q + 1, cb ^ 1);
;             const f32x4 g0 = *(const f32x4*)(gp + bj * HALF), g1 = *(const f32x4*)(gp + bj * HALF + 4);
;             f32x4 w0 = {1.f, 1.f, 1.f, 1.f}, w1 = w0, b0 = {0.f, 0.f, 0.f, 0.f}, b1 = b0;
;             if (stats) { w0 = *(const f32x4*)(lw + co); w1 = *(const f32x4*)(lw + co + 4); b0 = *(const f32x4*)(lb + co); b1 = *(const f32x4*)(lb + co + 4); }
; #pragma unroll
;             for (int m = 0; m < 4; ++m) { float* op = Xout + (size_t)(row0 + ai * HALF + m * 16) * D + co;
;                 f32x4 x0 = xa[cb][m], x1 = xb[cb][m];
;                 if (stats) { x0 = (x0 - st[ai][m].x) * st[ai][m].y * w0 + b0; x1 = (x1 - st[ai][m].x) * st[ai][m].y * w1 + b1; }
;                 *(f32x4*)op = x0 * ALPHA + g0 * acc[ai][bj][m][0]; *(f32x4*)(op + 4) = x1 * ALPHA + g1 * acc[ai][bj][m][1]; } }
	v_mov_b32_e32 v40, v204
	v_mov_b32_e32 v41, v205
	v_mov_b32_e32 v42, v206
	v_mov_b32_e32 v43, v207
	v_mov_b32_e32 v60, v208
	v_mov_b32_e32 v61, v209
	v_mov_b32_e32 v62, v210
	v_mov_b32_e32 v63, v211
	v_mov_b32_e32 v64, v212
	v_mov_b32_e32 v65, v213
	v_mov_b32_e32 v66, v214
	v_mov_b32_e32 v67, v215
	v_mov_b32_e32 v68, v216
	v_mov_b32_e32 v69, v217
	v_mov_b32_e32 v70, v218
	v_mov_b32_e32 v71, v219
	v_mov_b32_e32 v74, v220
	v_mov_b32_e32 v75, v221
	v_mov_b32_e32 v76, v222
	v_mov_b32_e32 v77, v223
	v_mov_b32_e32 v82, v226
	v_mov_b32_e32 v83, v227
	v_mov_b32_e32 v84, v228
	v_mov_b32_e32 v85, v229
	v_mov_b32_e32 v90, v230
	v_mov_b32_e32 v91, v231
	v_mov_b32_e32 v92, v232
	v_mov_b32_e32 v93, v233
	v_pk_fma_f32 v[78:79], v[78:79], v[32:33], v[36:37]
	v_pk_fma_f32 v[86:87], v[86:87], v[34:35], v[38:39]
	v_sub_f32_e32 v41, v41, v152
	v_sub_f32_e32 v40, v40, v152
	v_sub_f32_e32 v43, v43, v152
	v_sub_f32_e32 v42, v42, v152
	v_pk_mul_f32 v[42:43], v[152:153], v[42:43] op_sel:[1,0]
	v_pk_mul_f32 v[40:41], v[152:153], v[40:41] op_sel:[1,0]
	v_pk_mul_f32 v[86:87], v[86:87], s[30:31] op_sel_hi:[1,0]
	v_pk_mul_f32 v[78:79], v[78:79], s[30:31] op_sel_hi:[1,0]
	v_pk_fma_f32 v[40:41], v[40:41], v[44:45], v[48:49]
	v_pk_fma_f32 v[42:43], v[42:43], v[46:47], v[50:51]
	v_pk_fma_f32 v[28:29], v[28:29], v[52:53], v[78:79]
	v_pk_fma_f32 v[30:31], v[30:31], v[54:55], v[86:87]
	flat_store_dwordx4 v[96:97], v[28:31] offset:512
	s_nop 1
	v_pk_mul_f32 v[28:29], v[42:43], s[30:31] op_sel_hi:[1,0]
	v_pk_mul_f32 v[30:31], v[40:41], s[30:31] op_sel_hi:[1,0]
	v_pk_fma_f32 v[26:27], v[26:27], v[58:59], v[28:29]
	v_pk_fma_f32 v[24:25], v[24:25], v[56:57], v[30:31]
	flat_store_dwordx4 v[96:97], v[24:27] offset:528
	v_sub_f32_e32 v29, v65, v144
	v_sub_f32_e32 v28, v64, v144
	v_sub_f32_e32 v25, v61, v144
	v_sub_f32_e32 v24, v60, v144
	v_sub_f32_e32 v27, v63, v144
	v_sub_f32_e32 v26, v62, v144
	v_pk_mul_f32 v[26:27], v[144:145], v[26:27] op_sel:[1,0]
	v_pk_mul_f32 v[24:25], v[144:145], v[24:25] op_sel:[1,0]
	v_pk_fma_f32 v[26:27], v[26:27], v[34:35], v[38:39]
	v_pk_fma_f32 v[24:25], v[24:25], v[32:33], v[36:37]
	v_sub_f32_e32 v31, v67, v144
	v_sub_f32_e32 v30, v66, v144
	v_pk_mul_f32 v[30:31], v[144:145], v[30:31] op_sel:[1,0]
	v_pk_mul_f32 v[28:29], v[144:145], v[28:29] op_sel:[1,0]
	v_pk_mul_f32 v[26:27], v[26:27], s[30:31] op_sel_hi:[1,0]
	v_pk_mul_f32 v[24:25], v[24:25], s[30:31] op_sel_hi:[1,0]
	v_pk_fma_f32 v[28:29], v[28:29], v[44:45], v[48:49]
	v_pk_fma_f32 v[30:31], v[30:31], v[46:47], v[50:51]
	v_pk_fma_f32 v[20:21], v[20:21], v[52:53], v[24:25]
	v_pk_fma_f32 v[22:23], v[22:23], v[54:55], v[26:27]
	flat_store_dwordx4 v[88:89], v[20:23] offset:512
	s_nop 1
	v_pk_mul_f32 v[20:21], v[30:31], s[30:31] op_sel_hi:[1,0]
	v_pk_mul_f32 v[22:23], v[28:29], s[30:31] op_sel_hi:[1,0]
	v_pk_fma_f32 v[18:19], v[18:19], v[58:59], v[20:21]
	v_pk_fma_f32 v[16:17], v[16:17], v[56:57], v[22:23]
	flat_store_dwordx4 v[88:89], v[16:19] offset:528
	v_sub_f32_e32 v21, v75, v142
	v_sub_f32_e32 v20, v74, v142
	v_sub_f32_e32 v17, v69, v142
	v_sub_f32_e32 v16, v68, v142
	v_sub_f32_e32 v19, v71, v142
	v_sub_f32_e32 v18, v70, v142
	v_pk_mul_f32 v[18:19], v[142:143], v[18:19] op_sel:[1,0]
	v_pk_mul_f32 v[16:17], v[142:143], v[16:17] op_sel:[1,0]
	v_sub_f32_e32 v23, v77, v142
	v_sub_f32_e32 v22, v76, v142
	v_pk_fma_f32 v[16:17], v[16:17], v[32:33], v[36:37]
	v_pk_fma_f32 v[18:19], v[18:19], v[34:35], v[38:39]
	v_pk_mul_f32 v[22:23], v[142:143], v[22:23] op_sel:[1,0]
	v_pk_mul_f32 v[20:21], v[142:143], v[20:21] op_sel:[1,0]
	v_pk_fma_f32 v[22:23], v[22:23], v[46:47], v[50:51]
	v_pk_fma_f32 v[20:21], v[20:21], v[44:45], v[48:49]
	v_pk_mul_f32 v[18:19], v[18:19], s[30:31] op_sel_hi:[1,0]
	v_pk_mul_f32 v[16:17], v[16:17], s[30:31] op_sel_hi:[1,0]
	v_pk_fma_f32 v[14:15], v[14:15], v[54:55], v[18:19]
	v_pk_fma_f32 v[12:13], v[12:13], v[52:53], v[16:17]
	v_pk_mul_f32 v[16:17], v[22:23], s[30:31] op_sel_hi:[1,0]
	v_pk_mul_f32 v[18:19], v[20:21], s[30:31] op_sel_hi:[1,0]
	v_pk_fma_f32 v[10:11], v[10:11], v[58:59], v[16:17]
	v_pk_fma_f32 v[8:9], v[8:9], v[56:57], v[18:19]
	v_sub_f32_e32 v17, v83, v140
	v_sub_f32_e32 v16, v82, v140
	v_sub_f32_e32 v19, v85, v140
	v_sub_f32_e32 v18, v84, v140
	v_pk_mul_f32 v[18:19], v[140:141], v[18:19] op_sel:[1,0]
	v_pk_mul_f32 v[16:17], v[140:141], v[16:17] op_sel:[1,0]
	v_pk_fma_f32 v[18:19], v[18:19], v[34:35], v[38:39]
	v_pk_fma_f32 v[16:17], v[16:17], v[32:33], v[36:37]
	v_sub_f32_e32 v21, v91, v140
	v_sub_f32_e32 v20, v90, v140
	v_sub_f32_e32 v23, v93, v140
	v_sub_f32_e32 v22, v92, v140
	v_pk_mul_f32 v[22:23], v[140:141], v[22:23] op_sel:[1,0]
	v_pk_mul_f32 v[20:21], v[140:141], v[20:21] op_sel:[1,0]
	flat_store_dwordx4 v[80:81], v[12:15] offset:512
	flat_store_dwordx4 v[80:81], v[8:11] offset:528
	v_pk_fma_f32 v[20:21], v[20:21], v[44:45], v[48:49]
	v_pk_fma_f32 v[22:23], v[22:23], v[46:47], v[50:51]
	v_pk_mul_f32 v[8:9], v[18:19], s[30:31] op_sel_hi:[1,0]
	v_pk_mul_f32 v[10:11], v[16:17], s[30:31] op_sel_hi:[1,0]
	v_pk_fma_f32 v[6:7], v[6:7], v[54:55], v[8:9]
	v_pk_fma_f32 v[4:5], v[4:5], v[52:53], v[10:11]
	flat_store_dwordx4 v[72:73], v[4:7] offset:512
	s_nop 1
	v_pk_mul_f32 v[4:5], v[22:23], s[30:31] op_sel_hi:[1,0]
	v_pk_mul_f32 v[6:7], v[20:21], s[30:31] op_sel_hi:[1,0]
	v_pk_fma_f32 v[2:3], v[2:3], v[58:59], v[4:5]
	v_pk_fma_f32 v[0:1], v[0:1], v[56:57], v[6:7]
	flat_store_dwordx4 v[72:73], v[0:3] offset:528
	s_cbranch_vccnz .LBB0_1182
	s_andn2_b64 vcc, exec, s[10:11]
	s_cbranch_vccnz .LBB0_1181
	s_barrier
	s_branch .LBB0_1181

; #define EPIRES_LOAD(q_, buf_) do { const int bj_ = (q_) >> 1, ai_ = (q_) & 1; \
;             _Pragma("unroll") for (int m = 0; m < 4; ++m) { const float* xp = Xin + (size_t)(row0 + ai_ * HALF + m * 16) * D + col0 + bj_ * HALF; xa[buf_][m] = *(const f32x4*)xp; xb[buf_][m] = *(const f32x4*)(xp + 4); } } while (0)
;     __device__ __forceinline__ void operator()(const f32x4 (&acc)[2][2][4][2], const Unit& u, int wr, int wc, int fr, int fq) const {
;     ...
;         const int row0 = u.pm * BM + wr * 64 + fr, col0 = u.pn * BM + wc * 32 + 8 * fq;
;         const float* gp = gate + (size_t)((u.pm * BM) >> 11) * 6144 + col0;
;         f32x2_t st[2][4];
; #pragma unroll
;         for (int ai = 0; ai < 2; ++ai)
; #pragma unroll
;             for (int m = 0; m < 4; ++m) st[ai][m] = stats ? *(const f32x2_t*)(stats + 2 * (row0 + ai * HALF + m * 16)) : (f32x2_t){0.f, 1.f};
;         f32x4 xa[2][4], xb[2][4];
;     ...
;         EPIRES_LOAD(0, 0);
; #pragma unroll
;         for (int q = 0; q < 4; ++q) { const int bj = q >> 1, ai = q & 1, co = col0 + bj * HALF, cb = q & 1;
;             if (q + 1 < 4) EPIRES_LOAD(q + 1, cb ^ 1);
;             const f32x4 g0 = *(const f32x4*)(gp + bj * HALF), g1 = *(const f32x4*)(gp + bj * HALF + 4);
;             f32x4 w0 = {1.f, 1.f, 1.f, 1.f}, w1 = w0, b0 = {0.f, 0.f, 0.f, 0.f}, b1 = b0;
;             if (stats) { w0 = *(const f32x4*)(lw + co); w1 = *(const f32x4*)(lw + co + 4); b0 = *(const f32x4*)(lb + co); b1 = *(const f32x4*)(lb + co + 4); }
; #pragma unroll
;             for (int m = 0; m < 4; ++m) { float* op = Xout + (size_t)(row0 + ai * HALF + m * 16) * D + co;
;                 f32x4 x0 = xa[cb][m], x1 = xb[cb][m];
;                 if (stats) { x0 = (x0 - st[ai][m].x) * st[ai][m].y * w0 + b0; x1 = (x1 - st[ai][m].x) * st[ai][m].y * w1 + b1; }
;                 *(f32x4*)op = x0 * ALPHA + g0 * acc[ai][bj][m][0]; *(f32x4*)(op + 4) = x1 * ALPHA + g1 * acc[ai][bj][m][1]; } }
.LBB0_1407:
	v_lshl_add_u32 v140, s62, 8, v182
	v_lshl_add_u32 v142, s63, 8, v184
	v_ashrrev_i32_e32 v143, 31, v142
	v_lshlrev_b32_e32 v144, 1, v140
	v_ashrrev_i32_e32 v145, 31, v144
	v_lshlrev_b64 v[168:169], 2, v[142:143]
	v_ashrrev_i32_e32 v141, 31, v140
	v_lshl_add_u64 v[152:153], v[144:145], 2, s[16:17]
	v_lshl_add_u64 v[176:177], s[14:15], 0, v[168:169]
	v_lshlrev_b64 v[178:179], 12, v[140:141]
	s_ashr_i32 s40, s62, 3
	flat_load_dwordx2 v[158:159], v[152:153]
	v_lshl_add_u64 v[164:165], v[176:177], 0, v[178:179]
	s_mul_hi_i32 s41, s40, 0x6000
	s_mulk_i32 s40, 0x6000
	flat_load_dwordx4 v[188:191], v[164:165]
	flat_load_dwordx4 v[192:195], v[164:165] offset:16
	s_add_u32 s40, s52, s40
	s_addc_u32 s41, s53, s41
	v_lshl_add_u64 v[148:149], s[20:21], 0, v[168:169]
	v_lshl_add_u64 v[150:151], s[40:41], 0, v[168:169]
	v_lshl_add_u64 v[146:147], s[18:19], 0, v[168:169]
	flat_load_dwordx4 v[196:199], v[148:149]
	flat_load_dwordx4 v[200:203], v[146:147]
	flat_load_dwordx4 v[204:207], v[146:147] offset:16
	flat_load_dwordx4 v[208:211], v[148:149] offset:16
	flat_load_dwordx4 v[212:215], v[150:151]
	flat_load_dwordx4 v[216:219], v[150:151] offset:16
	v_or_b32_e32 v142, 16, v140
	v_ashrrev_i32_e32 v143, 31, v142
	v_lshlrev_b64 v[248:249], 12, v[142:143]
	flat_load_dwordx2 v[162:163], v[152:153] offset:128
	v_lshl_add_u64 v[170:171], v[176:177], 0, v[248:249]
	flat_load_dwordx4 v[220:223], v[170:171]
	flat_load_dwordx4 v[224:227], v[170:171] offset:16
	v_or_b32_e32 v142, 32, v140
	v_ashrrev_i32_e32 v143, 31, v142
	v_lshlrev_b64 v[250:251], 12, v[142:143]
	v_lshl_add_u64 v[172:173], v[176:177], 0, v[250:251]
	flat_load_dwordx2 v[160:161], v[152:153] offset:256
	flat_load_dwordx4 v[228:231], v[172:173]
	flat_load_dwordx4 v[232:235], v[172:173] offset:16
	flat_load_dwordx2 v[156:157], v[152:153] offset:384
	v_or_b32_e32 v140, 48, v140
	v_add_u32_e32 v154, 0x100, v144
	v_add_u32_e32 v166, 0x120, v144
	v_add_u32_e32 v174, 0x140, v144
	v_add_u32_e32 v144, 0x160, v144
	v_ashrrev_i32_e32 v141, 31, v140
	v_ashrrev_i32_e32 v155, 31, v154
	v_ashrrev_i32_e32 v167, 31, v166
	v_ashrrev_i32_e32 v175, 31, v174
	v_ashrrev_i32_e32 v145, 31, v144
	v_lshlrev_b64 v[252:253], 12, v[140:141]
	v_lshl_add_u64 v[180:181], v[178:179], 0, s[26:27]
	v_lshl_add_u64 v[140:141], s[14:15], 0, v[178:179]
	v_lshl_add_u64 v[142:143], v[154:155], 2, s[16:17]
	v_lshl_add_u64 v[236:237], v[166:167], 2, s[16:17]
	v_lshl_add_u64 v[238:239], v[174:175], 2, s[16:17]
	v_lshl_add_u64 v[240:241], v[144:145], 2, s[16:17]
	v_lshl_add_u64 v[174:175], v[176:177], 0, v[252:253]
	v_lshl_add_u64 v[154:155], v[176:177], 0, v[180:181]
	v_lshl_add_u64 v[166:167], v[140:141], 0, v[168:169]
	flat_load_dwordx2 v[152:153], v[142:143]
	flat_load_dwordx2 v[144:145], v[236:237]
	s_nop 0
	flat_load_dwordx2 v[142:143], v[238:239]
	flat_load_dwordx2 v[140:141], v[240:241]
	s_nop 0
	flat_load_dwordx4 v[236:239], v[174:175]
	flat_load_dwordx4 v[240:243], v[174:175] offset:16
	flat_load_dwordx4 v[244:247], v[154:155]
	s_and_b64 vcc, exec, s[4:5]
	s_mov_b64 s[4:5], -1
	s_waitcnt vmcnt(0) lgkmcnt(0)
	v_sub_f32_e32 v191, v191, v158
	v_sub_f32_e32 v190, v190, v158
	v_sub_f32_e32 v189, v189, v158
	v_sub_f32_e32 v188, v188, v158
	v_pk_mul_f32 v[188:189], v[158:159], v[188:189] op_sel:[1,0]
	v_pk_mul_f32 v[190:191], v[158:159], v[190:191] op_sel:[1,0]
	v_sub_f32_e32 v195, v195, v158
	v_sub_f32_e32 v194, v194, v158
	v_sub_f32_e32 v193, v193, v158
	v_sub_f32_e32 v192, v192, v158
	v_pk_fma_f32 v[190:191], v[190:191], v[202:203], v[198:199]
	v_pk_fma_f32 v[188:189], v[188:189], v[200:201], v[196:197]
	v_pk_mul_f32 v[192:193], v[158:159], v[192:193] op_sel:[1,0]
	v_pk_mul_f32 v[194:195], v[158:159], v[194:195] op_sel:[1,0]
	v_pk_mul_f32 v[188:189], v[188:189], s[34:35] op_sel_hi:[1,0]
	v_pk_mul_f32 v[190:191], v[190:191], s[34:35] op_sel_hi:[1,0]
	v_pk_fma_f32 v[194:195], v[194:195], v[206:207], v[210:211]
	v_pk_fma_f32 v[192:193], v[192:193], v[204:205], v[208:209]
	v_pk_fma_f32 v[126:127], v[126:127], v[214:215], v[190:191]
	v_pk_fma_f32 v[124:125], v[124:125], v[212:213], v[188:189]
	flat_store_dwordx4 v[166:167], v[124:127]
	v_sub_f32_e32 v189, v225, v162
	v_sub_f32_e32 v188, v224, v162
	v_pk_mul_f32 v[124:125], v[192:193], s[34:35] op_sel_hi:[1,0]
	v_pk_mul_f32 v[126:127], v[194:195], s[34:35] op_sel_hi:[1,0]
	v_pk_fma_f32 v[120:121], v[120:121], v[216:217], v[124:125]
	v_pk_fma_f32 v[122:123], v[122:123], v[218:219], v[126:127]
	flat_store_dwordx4 v[166:167], v[120:123] offset:16
	v_sub_f32_e32 v125, v221, v162
	v_sub_f32_e32 v124, v220, v162
	v_sub_f32_e32 v123, v223, v162
	v_sub_f32_e32 v122, v222, v162
	v_pk_mul_f32 v[124:125], v[162:163], v[124:125] op_sel:[1,0]
	v_pk_mul_f32 v[122:123], v[162:163], v[122:123] op_sel:[1,0]
	v_pk_fma_f32 v[124:125], v[124:125], v[200:201], v[196:197]
	v_pk_fma_f32 v[122:123], v[122:123], v[202:203], v[198:199]
	v_sub_f32_e32 v127, v227, v162
	v_sub_f32_e32 v126, v226, v162
	v_lshl_add_u64 v[120:121], s[14:15], 0, v[248:249]
	v_pk_mul_f32 v[188:189], v[162:163], v[188:189] op_sel:[1,0]
	v_pk_mul_f32 v[126:127], v[162:163], v[126:127] op_sel:[1,0]
	v_pk_mul_f32 v[124:125], v[124:125], s[34:35] op_sel_hi:[1,0]
	v_pk_mul_f32 v[122:123], v[122:123], s[34:35] op_sel_hi:[1,0]
	v_lshl_add_u64 v[120:121], v[120:121], 0, v[168:169]
	v_pk_fma_f32 v[126:127], v[126:127], v[206:207], v[210:211]
	v_pk_fma_f32 v[188:189], v[188:189], v[204:205], v[208:209]
	v_pk_fma_f32 v[118:119], v[118:119], v[214:215], v[122:123]
	v_pk_fma_f32 v[116:117], v[116:117], v[212:213], v[124:125]
	flat_store_dwordx4 v[120:121], v[116:119]
	v_sub_f32_e32 v123, v233, v160
	v_sub_f32_e32 v122, v232, v160
; #define EPIRES_LOAD(q_, buf_) do { const int bj_ = (q_) >> 1, ai_ = (q_) & 1; \
;             _Pragma("unroll") for (int m = 0; m < 4; ++m) { const float* xp = Xin + (size_t)(row0 + ai_ * HALF + m * 16) * D + col0 + bj_ * HALF; xa[buf_][m] = *(const f32x4*)xp; xb[buf_][m] = *(const f32x4*)(xp + 4); } } while (0)
;     __device__ __forceinline__ void operator()(const f32x4 (&acc)[2][2][4][2], const Unit& u, int wr, int wc, int fr, int fq) const {
;     ...
;         EPIRES_LOAD(0, 0);
; #pragma unroll
;         for (int q = 0; q < 4; ++q) { const int bj = q >> 1, ai = q & 1, co = col0 + bj * HALF, cb = q & 1;
;             if (q + 1 < 4) EPIRES_LOAD(q + 1, cb ^ 1);
;             const f32x4 g0 = *(const f32x4*)(gp + bj * HALF), g1 = *(const f32x4*)(gp + bj * HALF + 4);
;             f32x4 w0 = {1.f, 1.f, 1.f, 1.f}, w1 = w0, b0 = {0.f, 0.f, 0.f, 0.f}, b1 = b0;
;             if (stats) { w0 = *(const f32x4*)(lw + co); w1 = *(const f32x4*)(lw + co + 4); b0 = *(const f32x4*)(lb + co); b1 = *(const f32x4*)(lb + co + 4); }
; #pragma unroll
;             for (int m = 0; m < 4; ++m) { float* op = Xout + (size_t)(row0 + ai * HALF + m * 16) * D + co;
;                 f32x4 x0 = xa[cb][m], x1 = xb[cb][m];
;                 if (stats) { x0 = (x0 - st[ai][m].x) * st[ai][m].y * w0 + b0; x1 = (x1 - st[ai][m].x) * st[ai][m].y * w1 + b1; }
;                 *(f32x4*)op = x0 * ALPHA + g0 * acc[ai][bj][m][0]; *(f32x4*)(op + 4) = x1 * ALPHA + g1 * acc[ai][bj][m][1]; } }
	v_pk_mul_f32 v[116:117], v[188:189], s[34:35] op_sel_hi:[1,0]
	v_pk_mul_f32 v[118:119], v[126:127], s[34:35] op_sel_hi:[1,0]
	v_pk_fma_f32 v[112:113], v[112:113], v[216:217], v[116:117]
	v_pk_fma_f32 v[114:115], v[114:115], v[218:219], v[118:119]
	flat_store_dwordx4 v[120:121], v[112:115] offset:16
	v_sub_f32_e32 v117, v229, v160
	v_sub_f32_e32 v116, v228, v160
	v_sub_f32_e32 v115, v231, v160
	v_sub_f32_e32 v114, v230, v160
	v_pk_mul_f32 v[116:117], v[160:161], v[116:117] op_sel:[1,0]
	v_pk_mul_f32 v[114:115], v[160:161], v[114:115] op_sel:[1,0]
	v_pk_fma_f32 v[116:117], v[116:117], v[200:201], v[196:197]
	v_pk_fma_f32 v[114:115], v[114:115], v[202:203], v[198:199]
	v_sub_f32_e32 v119, v235, v160
	v_sub_f32_e32 v118, v234, v160
	v_lshl_add_u64 v[112:113], s[14:15], 0, v[250:251]
	v_pk_mul_f32 v[122:123], v[160:161], v[122:123] op_sel:[1,0]
	v_pk_mul_f32 v[118:119], v[160:161], v[118:119] op_sel:[1,0]
	v_pk_mul_f32 v[116:117], v[116:117], s[34:35] op_sel_hi:[1,0]
	v_pk_mul_f32 v[114:115], v[114:115], s[34:35] op_sel_hi:[1,0]
	v_lshl_add_u64 v[112:113], v[112:113], 0, v[168:169]
	v_pk_fma_f32 v[118:119], v[118:119], v[206:207], v[210:211]
	v_pk_fma_f32 v[122:123], v[122:123], v[204:205], v[208:209]
	v_pk_fma_f32 v[110:111], v[110:111], v[214:215], v[114:115]
	v_pk_fma_f32 v[108:109], v[108:109], v[212:213], v[116:117]
	flat_store_dwordx4 v[112:113], v[108:111]
	v_sub_f32_e32 v115, v241, v156
	v_sub_f32_e32 v114, v240, v156
	v_pk_mul_f32 v[108:109], v[122:123], s[34:35] op_sel_hi:[1,0]
	v_pk_mul_f32 v[110:111], v[118:119], s[34:35] op_sel_hi:[1,0]
	v_pk_fma_f32 v[104:105], v[104:105], v[216:217], v[108:109]
	v_pk_fma_f32 v[106:107], v[106:107], v[218:219], v[110:111]
	flat_store_dwordx4 v[112:113], v[104:107] offset:16
	v_sub_f32_e32 v109, v237, v156
	v_sub_f32_e32 v108, v236, v156
	v_sub_f32_e32 v107, v239, v156
	v_sub_f32_e32 v106, v238, v156
	v_pk_mul_f32 v[108:109], v[156:157], v[108:109] op_sel:[1,0]
	v_pk_mul_f32 v[106:107], v[156:157], v[106:107] op_sel:[1,0]
	v_pk_fma_f32 v[108:109], v[108:109], v[200:201], v[196:197]
	v_pk_fma_f32 v[106:107], v[106:107], v[202:203], v[198:199]
	v_sub_f32_e32 v111, v243, v156
	v_sub_f32_e32 v110, v242, v156
	v_lshl_add_u64 v[104:105], s[14:15], 0, v[252:253]
	v_pk_mul_f32 v[114:115], v[156:157], v[114:115] op_sel:[1,0]
	v_pk_mul_f32 v[110:111], v[156:157], v[110:111] op_sel:[1,0]
	v_pk_mul_f32 v[108:109], v[108:109], s[34:35] op_sel_hi:[1,0]
	v_pk_mul_f32 v[106:107], v[106:107], s[34:35] op_sel_hi:[1,0]
	v_lshl_add_u64 v[104:105], v[104:105], 0, v[168:169]
	v_pk_fma_f32 v[110:111], v[110:111], v[206:207], v[210:211]
	v_pk_fma_f32 v[114:115], v[114:115], v[204:205], v[208:209]
	v_pk_fma_f32 v[102:103], v[102:103], v[214:215], v[106:107]
	v_pk_fma_f32 v[100:101], v[100:101], v[212:213], v[108:109]
	flat_store_dwordx4 v[104:105], v[100:103]
	v_lshl_add_u64 v[118:119], v[178:179], 0, s[30:31]
	v_lshl_add_u64 v[126:127], v[178:179], 0, s[8:9]
	v_pk_mul_f32 v[100:101], v[114:115], s[34:35] op_sel_hi:[1,0]
	v_pk_mul_f32 v[102:103], v[110:111], s[34:35] op_sel_hi:[1,0]
	v_pk_fma_f32 v[96:97], v[96:97], v[216:217], v[100:101]
	v_pk_fma_f32 v[98:99], v[98:99], v[218:219], v[102:103]
	flat_store_dwordx4 v[104:105], v[96:99] offset:16
	flat_load_dwordx4 v[106:109], v[146:147]
	flat_load_dwordx4 v[114:117], v[148:149]
	flat_load_dwordx4 v[122:125], v[154:155] offset:16
	flat_load_dwordx4 v[188:191], v[146:147] offset:16
	flat_load_dwordx4 v[192:195], v[148:149] offset:16
	flat_load_dwordx4 v[196:199], v[150:151]
	flat_load_dwordx4 v[200:203], v[150:151] offset:16
	v_lshl_add_u64 v[110:111], v[178:179], 0, s[28:29]
	v_lshl_add_u64 v[98:99], v[176:177], 0, v[110:111]
	flat_load_dwordx4 v[204:207], v[98:99]
	flat_load_dwordx4 v[208:211], v[98:99] offset:16
	v_lshl_add_u64 v[100:101], v[176:177], 0, v[118:119]
	flat_load_dwordx4 v[212:215], v[100:101]
	flat_load_dwordx4 v[216:219], v[100:101] offset:16
	v_lshl_add_u64 v[102:103], v[176:177], 0, v[126:127]
	flat_load_dwordx4 v[176:179], v[102:103]
	flat_load_dwordx4 v[220:223], v[102:103] offset:16
	flat_load_dwordx4 v[224:227], v[164:165] offset:512
	v_lshl_add_u64 v[96:97], s[14:15], 0, v[180:181]
	v_sub_f32_e32 v181, v245, v152
	v_sub_f32_e32 v180, v244, v152
	v_sub_f32_e32 v229, v247, v152
	v_sub_f32_e32 v228, v246, v152
	v_pk_mul_f32 v[228:229], v[152:153], v[228:229] op_sel:[1,0]
	v_pk_mul_f32 v[180:181], v[152:153], v[180:181] op_sel:[1,0]
	v_lshl_add_u64 v[96:97], v[96:97], 0, v[168:169]
	s_waitcnt vmcnt(0) lgkmcnt(0)
; #define EPIRES_LOAD(q_, buf_) do { const int bj_ = (q_) >> 1, ai_ = (q_) & 1; \
;             _Pragma("unroll") for (int m = 0; m < 4; ++m) { const float* xp = Xin + (size_t)(row0 + ai_ * HALF + m * 16) * D + col0 + bj_ * HALF; xa[buf_][m] = *(const f32x4*)xp; xb[buf_][m] = *(const f32x4*)(xp + 4); } } while (0)
;     __device__ __forceinline__ void operator()(const f32x4 (&acc)[2][2][4][2], const Unit& u, int wr, int wc, int fr, int fq) const {
;     ...
;         EPIRES_LOAD(0, 0);
; #pragma unroll
;         for (int q = 0; q < 4; ++q) { const int bj = q >> 1, ai = q & 1, co = col0 + bj * HALF, cb = q & 1;
;             if (q + 1 < 4) EPIRES_LOAD(q + 1, cb ^ 1);
;             const f32x4 g0 = *(const f32x4*)(gp + bj * HALF), g1 = *(const f32x4*)(gp + bj * HALF + 4);
;             f32x4 w0 = {1.f, 1.f, 1.f, 1.f}, w1 = w0, b0 = {0.f, 0.f, 0.f, 0.f}, b1 = b0;
;             if (stats) { w0 = *(const f32x4*)(lw + co); w1 = *(const f32x4*)(lw + co + 4); b0 = *(const f32x4*)(lb + co); b1 = *(const f32x4*)(lb + co + 4); }
; #pragma unroll
;             for (int m = 0; m < 4; ++m) { float* op = Xout + (size_t)(row0 + ai * HALF + m * 16) * D + co;
;                 f32x4 x0 = xa[cb][m], x1 = xb[cb][m];
;                 if (stats) { x0 = (x0 - st[ai][m].x) * st[ai][m].y * w0 + b0; x1 = (x1 - st[ai][m].x) * st[ai][m].y * w1 + b1; }
;                 *(f32x4*)op = x0 * ALPHA + g0 * acc[ai][bj][m][0]; *(f32x4*)(op + 4) = x1 * ALPHA + g1 * acc[ai][bj][m][1]; } }
	v_pk_fma_f32 v[180:181], v[180:181], v[106:107], v[114:115]
	v_pk_fma_f32 v[228:229], v[228:229], v[108:109], v[116:117]
	v_sub_f32_e32 v123, v123, v152
	v_sub_f32_e32 v122, v122, v152
	v_sub_f32_e32 v125, v125, v152
	v_sub_f32_e32 v124, v124, v152
	v_pk_mul_f32 v[124:125], v[152:153], v[124:125] op_sel:[1,0]
	v_pk_mul_f32 v[122:123], v[152:153], v[122:123] op_sel:[1,0]
	v_pk_mul_f32 v[228:229], v[228:229], s[34:35] op_sel_hi:[1,0]
	v_pk_mul_f32 v[180:181], v[180:181], s[34:35] op_sel_hi:[1,0]
	v_pk_fma_f32 v[122:123], v[122:123], v[188:189], v[192:193]
	v_pk_fma_f32 v[124:125], v[124:125], v[190:191], v[194:195]
	v_pk_fma_f32 v[92:93], v[92:93], v[196:197], v[180:181]
	v_pk_fma_f32 v[94:95], v[94:95], v[198:199], v[228:229]
	flat_store_dwordx4 v[96:97], v[92:95]
	s_nop 1
	v_pk_mul_f32 v[92:93], v[124:125], s[34:35] op_sel_hi:[1,0]
	v_pk_mul_f32 v[94:95], v[122:123], s[34:35] op_sel_hi:[1,0]
	v_pk_fma_f32 v[90:91], v[90:91], v[202:203], v[92:93]
	v_pk_fma_f32 v[88:89], v[88:89], v[200:201], v[94:95]
	flat_store_dwordx4 v[96:97], v[88:91] offset:16
	v_sub_f32_e32 v93, v207, v144
	v_sub_f32_e32 v92, v206, v144
	v_sub_f32_e32 v91, v205, v144
	v_sub_f32_e32 v90, v204, v144
	v_pk_mul_f32 v[92:93], v[144:145], v[92:93] op_sel:[1,0]
	v_pk_mul_f32 v[90:91], v[144:145], v[90:91] op_sel:[1,0]
	v_lshl_add_u64 v[88:89], s[14:15], 0, v[110:111]
	v_pk_fma_f32 v[90:91], v[90:91], v[106:107], v[114:115]
	v_pk_fma_f32 v[92:93], v[92:93], v[108:109], v[116:117]
	v_sub_f32_e32 v95, v209, v144
	v_sub_f32_e32 v94, v208, v144
	v_sub_f32_e32 v111, v211, v144
	v_sub_f32_e32 v110, v210, v144
	v_pk_mul_f32 v[110:111], v[144:145], v[110:111] op_sel:[1,0]
	v_pk_mul_f32 v[94:95], v[144:145], v[94:95] op_sel:[1,0]
	v_pk_mul_f32 v[92:93], v[92:93], s[34:35] op_sel_hi:[1,0]
	v_pk_mul_f32 v[90:91], v[90:91], s[34:35] op_sel_hi:[1,0]
	v_lshl_add_u64 v[88:89], v[88:89], 0, v[168:169]
	v_pk_fma_f32 v[94:95], v[94:95], v[188:189], v[192:193]
	v_pk_fma_f32 v[110:111], v[110:111], v[190:191], v[194:195]
	v_pk_fma_f32 v[84:85], v[84:85], v[196:197], v[90:91]
	v_pk_fma_f32 v[86:87], v[86:87], v[198:199], v[92:93]
	flat_store_dwordx4 v[88:89], v[84:87]
	v_sub_f32_e32 v91, v219, v142
	v_sub_f32_e32 v90, v218, v142
	v_pk_mul_f32 v[84:85], v[110:111], s[34:35] op_sel_hi:[1,0]
	v_pk_mul_f32 v[86:87], v[94:95], s[34:35] op_sel_hi:[1,0]
	v_pk_fma_f32 v[82:83], v[82:83], v[202:203], v[84:85]
	v_pk_fma_f32 v[80:81], v[80:81], v[200:201], v[86:87]
	flat_store_dwordx4 v[88:89], v[80:83] offset:16
	v_sub_f32_e32 v85, v215, v142
	v_sub_f32_e32 v84, v214, v142
	v_sub_f32_e32 v83, v213, v142
	v_sub_f32_e32 v82, v212, v142
	v_pk_mul_f32 v[84:85], v[142:143], v[84:85] op_sel:[1,0]
	v_pk_mul_f32 v[82:83], v[142:143], v[82:83] op_sel:[1,0]
	v_pk_fma_f32 v[84:85], v[84:85], v[108:109], v[116:117]
	v_pk_fma_f32 v[82:83], v[82:83], v[106:107], v[114:115]
	v_sub_f32_e32 v87, v217, v142
	v_sub_f32_e32 v86, v216, v142
	v_lshl_add_u64 v[80:81], s[14:15], 0, v[118:119]
	v_pk_mul_f32 v[90:91], v[142:143], v[90:91] op_sel:[1,0]
	v_pk_mul_f32 v[86:87], v[142:143], v[86:87] op_sel:[1,0]
	v_pk_mul_f32 v[84:85], v[84:85], s[34:35] op_sel_hi:[1,0]
	v_pk_mul_f32 v[82:83], v[82:83], s[34:35] op_sel_hi:[1,0]
	v_lshl_add_u64 v[80:81], v[80:81], 0, v[168:169]
	v_pk_fma_f32 v[86:87], v[86:87], v[188:189], v[192:193]
	v_pk_fma_f32 v[90:91], v[90:91], v[190:191], v[194:195]
	v_pk_fma_f32 v[76:77], v[76:77], v[196:197], v[82:83]
	v_pk_fma_f32 v[78:79], v[78:79], v[198:199], v[84:85]
	flat_store_dwordx4 v[80:81], v[76:79]
	v_sub_f32_e32 v83, v223, v140
	v_sub_f32_e32 v82, v222, v140
	v_pk_mul_f32 v[76:77], v[90:91], s[34:35] op_sel_hi:[1,0]
	v_pk_mul_f32 v[78:79], v[86:87], s[34:35] op_sel_hi:[1,0]
	v_pk_fma_f32 v[74:75], v[74:75], v[202:203], v[76:77]
	v_pk_fma_f32 v[72:73], v[72:73], v[200:201], v[78:79]
	flat_store_dwordx4 v[80:81], v[72:75] offset:16
	v_sub_f32_e32 v77, v179, v140
	v_sub_f32_e32 v76, v178, v140
	v_sub_f32_e32 v75, v177, v140
	v_sub_f32_e32 v74, v176, v140
	v_pk_mul_f32 v[76:77], v[140:141], v[76:77] op_sel:[1,0]
	v_pk_mul_f32 v[74:75], v[140:141], v[74:75] op_sel:[1,0]
	v_pk_fma_f32 v[76:77], v[76:77], v[108:109], v[116:117]
	v_pk_fma_f32 v[74:75], v[74:75], v[106:107], v[114:115]
	v_sub_f32_e32 v79, v221, v140
	v_sub_f32_e32 v78, v220, v140
	v_lshl_add_u64 v[72:73], s[14:15], 0, v[126:127]
	v_pk_mul_f32 v[82:83], v[140:141], v[82:83] op_sel:[1,0]
	v_pk_mul_f32 v[78:79], v[140:141], v[78:79] op_sel:[1,0]
	v_pk_mul_f32 v[76:77], v[76:77], s[34:35] op_sel_hi:[1,0]
	v_pk_mul_f32 v[74:75], v[74:75], s[34:35] op_sel_hi:[1,0]
	v_lshl_add_u64 v[72:73], v[72:73], 0, v[168:169]
	v_pk_fma_f32 v[78:79], v[78:79], v[188:189], v[192:193]
	v_pk_fma_f32 v[82:83], v[82:83], v[190:191], v[194:195]
	v_pk_fma_f32 v[68:69], v[68:69], v[196:197], v[74:75]
	v_pk_fma_f32 v[70:71], v[70:71], v[198:199], v[76:77]
	flat_store_dwordx4 v[72:73], v[68:71]
	v_sub_f32_e32 v87, v227, v158
	v_sub_f32_e32 v86, v226, v158
	v_pk_mul_f32 v[68:69], v[82:83], s[34:35] op_sel_hi:[1,0]
	v_pk_mul_f32 v[70:71], v[78:79], s[34:35] op_sel_hi:[1,0]
	v_pk_fma_f32 v[66:67], v[66:67], v[202:203], v[68:69]
	v_pk_fma_f32 v[64:65], v[64:65], v[200:201], v[70:71]
	flat_store_dwordx4 v[72:73], v[64:67] offset:16
	flat_load_dwordx4 v[200:203], v[154:155] offset:512
	flat_load_dwordx4 v[204:207], v[154:155] offset:528
	flat_load_dwordx4 v[208:211], v[98:99] offset:512
	flat_load_dwordx4 v[212:215], v[98:99] offset:528
	flat_load_dwordx4 v[216:219], v[100:101] offset:512
	flat_load_dwordx4 v[220:223], v[100:101] offset:528
	flat_load_dwordx4 v[226:229], v[102:103] offset:512
	flat_load_dwordx4 v[230:233], v[102:103] offset:528
	flat_load_dwordx4 v[64:67], v[146:147] offset:512
	s_nop 0
	flat_load_dwordx4 v[68:71], v[148:149] offset:512
	flat_load_dwordx4 v[74:77], v[164:165] offset:528
	flat_load_dwordx4 v[82:85], v[146:147] offset:528
	flat_load_dwordx4 v[90:93], v[148:149] offset:528
	flat_load_dwordx4 v[106:109], v[150:151] offset:512
	flat_load_dwordx4 v[114:117], v[150:151] offset:528
	flat_load_dwordx4 v[122:125], v[170:171] offset:512
	s_nop 0
	flat_load_dwordx4 v[168:171], v[170:171] offset:528
	s_nop 0
	flat_load_dwordx4 v[176:179], v[172:173] offset:512
	flat_load_dwordx4 v[188:191], v[172:173] offset:528
	flat_load_dwordx4 v[192:195], v[174:175] offset:512
	s_nop 0
	flat_load_dwordx4 v[172:175], v[174:175] offset:528
	s_nop 0
	v_sub_f32_e32 v79, v225, v158
	v_sub_f32_e32 v78, v224, v158
	v_pk_mul_f32 v[86:87], v[158:159], v[86:87] op_sel:[1,0]
	v_pk_mul_f32 v[78:79], v[158:159], v[78:79] op_sel:[1,0]
	s_waitcnt vmcnt(0) lgkmcnt(0)
; #define EPIRES_LOAD(q_, buf_) do { const int bj_ = (q_) >> 1, ai_ = (q_) & 1; \
;             _Pragma("unroll") for (int m = 0; m < 4; ++m) { const float* xp = Xin + (size_t)(row0 + ai_ * HALF + m * 16) * D + col0 + bj_ * HALF; xa[buf_][m] = *(const f32x4*)xp; xb[buf_][m] = *(const f32x4*)(xp + 4); } } while (0)
;     __device__ __forceinline__ void operator()(const f32x4 (&acc)[2][2][4][2], const Unit& u, int wr, int wc, int fr, int fq) const {
;     ...
;         EPIRES_LOAD(0, 0);
; #pragma unroll
;         for (int q = 0; q < 4; ++q) { const int bj = q >> 1, ai = q & 1, co = col0 + bj * HALF, cb = q & 1;
;             if (q + 1 < 4) EPIRES_LOAD(q + 1, cb ^ 1);
;             const f32x4 g0 = *(const f32x4*)(gp + bj * HALF), g1 = *(const f32x4*)(gp + bj * HALF + 4);
;             f32x4 w0 = {1.f, 1.f, 1.f, 1.f}, w1 = w0, b0 = {0.f, 0.f, 0.f, 0.f}, b1 = b0;
;             if (stats) { w0 = *(const f32x4*)(lw + co); w1 = *(const f32x4*)(lw + co + 4); b0 = *(const f32x4*)(lb + co); b1 = *(const f32x4*)(lb + co + 4); }
; #pragma unroll
;             for (int m = 0; m < 4; ++m) { float* op = Xout + (size_t)(row0 + ai * HALF + m * 16) * D + co;
;                 f32x4 x0 = xa[cb][m], x1 = xb[cb][m];
;                 if (stats) { x0 = (x0 - st[ai][m].x) * st[ai][m].y * w0 + b0; x1 = (x1 - st[ai][m].x) * st[ai][m].y * w1 + b1; }
;                 *(f32x4*)op = x0 * ALPHA + g0 * acc[ai][bj][m][0]; *(f32x4*)(op + 4) = x1 * ALPHA + g1 * acc[ai][bj][m][1]; } }
	v_mov_b32_e32 v196, v200
	v_mov_b32_e32 v197, v201
	v_mov_b32_e32 v198, v202
	v_mov_b32_e32 v199, v203
	v_pk_fma_f32 v[86:87], v[86:87], v[66:67], v[70:71]
	v_pk_fma_f32 v[78:79], v[78:79], v[64:65], v[68:69]
	v_sub_f32_e32 v75, v75, v158
	v_sub_f32_e32 v74, v74, v158
	v_sub_f32_e32 v77, v77, v158
	v_sub_f32_e32 v76, v76, v158
	v_pk_mul_f32 v[76:77], v[158:159], v[76:77] op_sel:[1,0]
	v_pk_mul_f32 v[74:75], v[158:159], v[74:75] op_sel:[1,0]
	v_pk_mul_f32 v[86:87], v[86:87], s[34:35] op_sel_hi:[1,0]
	v_pk_mul_f32 v[78:79], v[78:79], s[34:35] op_sel_hi:[1,0]
	v_pk_fma_f32 v[74:75], v[74:75], v[82:83], v[90:91]
	v_pk_fma_f32 v[76:77], v[76:77], v[84:85], v[92:93]
	v_pk_fma_f32 v[60:61], v[60:61], v[106:107], v[78:79]
	v_pk_fma_f32 v[62:63], v[62:63], v[108:109], v[86:87]
	flat_store_dwordx4 v[166:167], v[60:63] offset:512
	v_sub_f32_e32 v79, v197, v152
	v_sub_f32_e32 v78, v196, v152
	v_pk_mul_f32 v[60:61], v[76:77], s[34:35] op_sel_hi:[1,0]
	v_pk_mul_f32 v[62:63], v[74:75], s[34:35] op_sel_hi:[1,0]
	v_pk_fma_f32 v[58:59], v[58:59], v[116:117], v[60:61]
	v_pk_fma_f32 v[56:57], v[56:57], v[114:115], v[62:63]
	flat_store_dwordx4 v[166:167], v[56:59] offset:528
	v_sub_f32_e32 v61, v169, v162
	v_sub_f32_e32 v60, v168, v162
	v_sub_f32_e32 v57, v123, v162
	v_sub_f32_e32 v56, v122, v162
	v_sub_f32_e32 v59, v125, v162
	v_sub_f32_e32 v58, v124, v162
	v_pk_mul_f32 v[58:59], v[162:163], v[58:59] op_sel:[1,0]
	v_pk_mul_f32 v[56:57], v[162:163], v[56:57] op_sel:[1,0]
	v_pk_fma_f32 v[58:59], v[58:59], v[66:67], v[70:71]
	v_pk_fma_f32 v[56:57], v[56:57], v[64:65], v[68:69]
	v_sub_f32_e32 v63, v171, v162
	v_sub_f32_e32 v62, v170, v162
	v_pk_mul_f32 v[62:63], v[162:163], v[62:63] op_sel:[1,0]
	v_pk_mul_f32 v[60:61], v[162:163], v[60:61] op_sel:[1,0]
	v_pk_mul_f32 v[58:59], v[58:59], s[34:35] op_sel_hi:[1,0]
	v_pk_mul_f32 v[56:57], v[56:57], s[34:35] op_sel_hi:[1,0]
	v_pk_fma_f32 v[60:61], v[60:61], v[82:83], v[90:91]
	v_pk_fma_f32 v[62:63], v[62:63], v[84:85], v[92:93]
	v_pk_fma_f32 v[52:53], v[52:53], v[106:107], v[56:57]
	v_pk_fma_f32 v[54:55], v[54:55], v[108:109], v[58:59]
	flat_store_dwordx4 v[120:121], v[52:55] offset:512
	v_sub_f32_e32 v87, v199, v152
	v_sub_f32_e32 v86, v198, v152
	v_pk_mul_f32 v[52:53], v[62:63], s[34:35] op_sel_hi:[1,0]
	v_pk_mul_f32 v[54:55], v[60:61], s[34:35] op_sel_hi:[1,0]
	v_pk_fma_f32 v[50:51], v[50:51], v[116:117], v[52:53]
	v_pk_fma_f32 v[48:49], v[48:49], v[114:115], v[54:55]
	flat_store_dwordx4 v[120:121], v[48:51] offset:528
	v_sub_f32_e32 v53, v189, v160
	v_sub_f32_e32 v52, v188, v160
	v_sub_f32_e32 v49, v177, v160
	v_sub_f32_e32 v48, v176, v160
	v_sub_f32_e32 v51, v179, v160
	v_sub_f32_e32 v50, v178, v160
	v_pk_mul_f32 v[50:51], v[160:161], v[50:51] op_sel:[1,0]
	v_pk_mul_f32 v[48:49], v[160:161], v[48:49] op_sel:[1,0]
	v_pk_fma_f32 v[50:51], v[50:51], v[66:67], v[70:71]
	v_pk_fma_f32 v[48:49], v[48:49], v[64:65], v[68:69]
	v_sub_f32_e32 v55, v191, v160
	v_sub_f32_e32 v54, v190, v160
	v_pk_mul_f32 v[54:55], v[160:161], v[54:55] op_sel:[1,0]
	v_pk_mul_f32 v[52:53], v[160:161], v[52:53] op_sel:[1,0]
	v_pk_mul_f32 v[50:51], v[50:51], s[34:35] op_sel_hi:[1,0]
	v_pk_mul_f32 v[48:49], v[48:49], s[34:35] op_sel_hi:[1,0]
	v_pk_fma_f32 v[52:53], v[52:53], v[82:83], v[90:91]
	v_pk_fma_f32 v[54:55], v[54:55], v[84:85], v[92:93]
	v_pk_fma_f32 v[44:45], v[44:45], v[106:107], v[48:49]
	v_pk_fma_f32 v[46:47], v[46:47], v[108:109], v[50:51]
	flat_store_dwordx4 v[112:113], v[44:47] offset:512
	v_pk_mul_f32 v[86:87], v[152:153], v[86:87] op_sel:[1,0]
	v_pk_mul_f32 v[78:79], v[152:153], v[78:79] op_sel:[1,0]
	v_pk_mul_f32 v[44:45], v[54:55], s[34:35] op_sel_hi:[1,0]
	v_pk_mul_f32 v[46:47], v[52:53], s[34:35] op_sel_hi:[1,0]
	v_pk_fma_f32 v[42:43], v[42:43], v[116:117], v[44:45]
	v_pk_fma_f32 v[40:41], v[40:41], v[114:115], v[46:47]
	flat_store_dwordx4 v[112:113], v[40:43] offset:528
	v_sub_f32_e32 v45, v173, v156
	v_sub_f32_e32 v44, v172, v156
	v_sub_f32_e32 v41, v193, v156
	v_sub_f32_e32 v40, v192, v156
	v_sub_f32_e32 v43, v195, v156
	v_sub_f32_e32 v42, v194, v156
	v_pk_mul_f32 v[42:43], v[156:157], v[42:43] op_sel:[1,0]
	v_pk_mul_f32 v[40:41], v[156:157], v[40:41] op_sel:[1,0]
	v_pk_fma_f32 v[42:43], v[42:43], v[66:67], v[70:71]
	v_pk_fma_f32 v[40:41], v[40:41], v[64:65], v[68:69]
	v_sub_f32_e32 v47, v175, v156
	v_sub_f32_e32 v46, v174, v156
	v_pk_mul_f32 v[46:47], v[156:157], v[46:47] op_sel:[1,0]
	v_pk_mul_f32 v[44:45], v[156:157], v[44:45] op_sel:[1,0]
	v_pk_mul_f32 v[42:43], v[42:43], s[34:35] op_sel_hi:[1,0]
	v_pk_mul_f32 v[40:41], v[40:41], s[34:35] op_sel_hi:[1,0]
	v_pk_fma_f32 v[44:45], v[44:45], v[82:83], v[90:91]
	v_pk_fma_f32 v[46:47], v[46:47], v[84:85], v[92:93]
	v_pk_fma_f32 v[36:37], v[36:37], v[106:107], v[40:41]
	v_pk_fma_f32 v[38:39], v[38:39], v[108:109], v[42:43]
	flat_store_dwordx4 v[104:105], v[36:39] offset:512
	s_nop 1
	v_pk_mul_f32 v[36:37], v[46:47], s[34:35] op_sel_hi:[1,0]
	v_pk_mul_f32 v[38:39], v[44:45], s[34:35] op_sel_hi:[1,0]
	v_pk_fma_f32 v[34:35], v[34:35], v[116:117], v[36:37]
	v_pk_fma_f32 v[32:33], v[32:33], v[114:115], v[38:39]
	flat_store_dwordx4 v[104:105], v[32:35] offset:528
	flat_load_dwordx4 v[32:35], v[146:147] offset:512
	s_nop 0
	flat_load_dwordx4 v[36:39], v[148:149] offset:512
	flat_load_dwordx4 v[44:47], v[146:147] offset:528
	flat_load_dwordx4 v[48:51], v[148:149] offset:528
	flat_load_dwordx4 v[52:55], v[150:151] offset:512
	flat_load_dwordx4 v[56:59], v[150:151] offset:528
	s_waitcnt vmcnt(0) lgkmcnt(0)
; #define EPIRES_LOAD(q_, buf_) do { const int bj_ = (q_) >> 1, ai_ = (q_) & 1; \
;             _Pragma("unroll") for (int m = 0; m < 4; ++m) { const float* xp = Xin + (size_t)(row0 + ai_ * HALF + m * 16) * D + col0 + bj_ * HALF; xa[buf_][m] = *(const f32x4*)xp; xb[buf_][m] = *(const f32x4*)(xp + 4); } } while (0)
;     __device__ __forceinline__ void operator()(const f32x4 (&acc)[2][2][4][2], const Unit& u, int wr, int wc, int fr, int fq) const {
;     ...
;         EPIRES_LOAD(0, 0);
; #pragma unroll
;         for (int q = 0; q < 4; ++q) { const int bj = q >> 1, ai = q & 1, co = col0 + bj * HALF, cb = q & 1;
;             if (q + 1 < 4) EPIRES_LOAD(q + 1, cb ^ 1);
;             const f32x4 g0 = *(const f32x4*)(gp + bj * HALF), g1 = *(const f32x4*)(gp + bj * HALF + 4);
;             f32x4 w0 = {1.f, 1.f, 1.f, 1.f}, w1 = w0, b0 = {0.f, 0.f, 0.f, 0.f}, b1 = b0;
;             if (stats) { w0 = *(const f32x4*)(lw + co); w1 = *(const f32x4*)(lw + co + 4); b0 = *(const f32x4*)(lb + co); b1 = *(const f32x4*)(lb + co + 4); }
; #pragma unroll
;             for (int m = 0; m < 4; ++m) { float* op = Xout + (size_t)(row0 + ai * HALF + m * 16) * D + co;
;                 f32x4 x0 = xa[cb][m], x1 = xb[cb][m];
;                 if (stats) { x0 = (x0 - st[ai][m].x) * st[ai][m].y * w0 + b0; x1 = (x1 - st[ai][m].x) * st[ai][m].y * w1 + b1; }
;                 *(f32x4*)op = x0 * ALPHA + g0 * acc[ai][bj][m][0]; *(f32x4*)(op + 4) = x1 * ALPHA + g1 * acc[ai][bj][m][1]; } }
	v_mov_b32_e32 v40, v204
	v_mov_b32_e32 v41, v205
	v_mov_b32_e32 v42, v206
	v_mov_b32_e32 v43, v207
	v_mov_b32_e32 v60, v208
	v_mov_b32_e32 v61, v209
	v_mov_b32_e32 v62, v210
	v_mov_b32_e32 v63, v211
	v_mov_b32_e32 v64, v212
	v_mov_b32_e32 v65, v213
	v_mov_b32_e32 v66, v214
	v_mov_b32_e32 v67, v215
	v_mov_b32_e32 v68, v216
	v_mov_b32_e32 v69, v217
	v_mov_b32_e32 v70, v218
	v_mov_b32_e32 v71, v219
	v_mov_b32_e32 v74, v220
	v_mov_b32_e32 v75, v221
	v_mov_b32_e32 v76, v222
	v_mov_b32_e32 v77, v223
	v_mov_b32_e32 v82, v226
	v_mov_b32_e32 v83, v227
	v_mov_b32_e32 v84, v228
	v_mov_b32_e32 v85, v229
	v_mov_b32_e32 v90, v230
	v_mov_b32_e32 v91, v231
	v_mov_b32_e32 v92, v232
	v_mov_b32_e32 v93, v233
	v_pk_fma_f32 v[78:79], v[78:79], v[32:33], v[36:37]
	v_pk_fma_f32 v[86:87], v[86:87], v[34:35], v[38:39]
	v_sub_f32_e32 v41, v41, v152
	v_sub_f32_e32 v40, v40, v152
	v_sub_f32_e32 v43, v43, v152
	v_sub_f32_e32 v42, v42, v152
	v_pk_mul_f32 v[42:43], v[152:153], v[42:43] op_sel:[1,0]
	v_pk_mul_f32 v[40:41], v[152:153], v[40:41] op_sel:[1,0]
	v_pk_mul_f32 v[86:87], v[86:87], s[34:35] op_sel_hi:[1,0]
	v_pk_mul_f32 v[78:79], v[78:79], s[34:35] op_sel_hi:[1,0]
	v_pk_fma_f32 v[40:41], v[40:41], v[44:45], v[48:49]
	v_pk_fma_f32 v[42:43], v[42:43], v[46:47], v[50:51]
	v_pk_fma_f32 v[28:29], v[28:29], v[52:53], v[78:79]
	v_pk_fma_f32 v[30:31], v[30:31], v[54:55], v[86:87]
	flat_store_dwordx4 v[96:97], v[28:31] offset:512
	s_nop 1
	v_pk_mul_f32 v[28:29], v[42:43], s[34:35] op_sel_hi:[1,0]
	v_pk_mul_f32 v[30:31], v[40:41], s[34:35] op_sel_hi:[1,0]
	v_pk_fma_f32 v[26:27], v[26:27], v[58:59], v[28:29]
	v_pk_fma_f32 v[24:25], v[24:25], v[56:57], v[30:31]
	flat_store_dwordx4 v[96:97], v[24:27] offset:528
	v_sub_f32_e32 v29, v65, v144
	v_sub_f32_e32 v28, v64, v144
	v_sub_f32_e32 v25, v61, v144
	v_sub_f32_e32 v24, v60, v144
	v_sub_f32_e32 v27, v63, v144
	v_sub_f32_e32 v26, v62, v144
	v_pk_mul_f32 v[26:27], v[144:145], v[26:27] op_sel:[1,0]
	v_pk_mul_f32 v[24:25], v[144:145], v[24:25] op_sel:[1,0]
	v_pk_fma_f32 v[26:27], v[26:27], v[34:35], v[38:39]
	v_pk_fma_f32 v[24:25], v[24:25], v[32:33], v[36:37]
	v_sub_f32_e32 v31, v67, v144
	v_sub_f32_e32 v30, v66, v144
	v_pk_mul_f32 v[30:31], v[144:145], v[30:31] op_sel:[1,0]
	v_pk_mul_f32 v[28:29], v[144:145], v[28:29] op_sel:[1,0]
	v_pk_mul_f32 v[26:27], v[26:27], s[34:35] op_sel_hi:[1,0]
	v_pk_mul_f32 v[24:25], v[24:25], s[34:35] op_sel_hi:[1,0]
	v_pk_fma_f32 v[28:29], v[28:29], v[44:45], v[48:49]
	v_pk_fma_f32 v[30:31], v[30:31], v[46:47], v[50:51]
	v_pk_fma_f32 v[20:21], v[20:21], v[52:53], v[24:25]
	v_pk_fma_f32 v[22:23], v[22:23], v[54:55], v[26:27]
	flat_store_dwordx4 v[88:89], v[20:23] offset:512
	s_nop 1
	v_pk_mul_f32 v[20:21], v[30:31], s[34:35] op_sel_hi:[1,0]
	v_pk_mul_f32 v[22:23], v[28:29], s[34:35] op_sel_hi:[1,0]
	v_pk_fma_f32 v[18:19], v[18:19], v[58:59], v[20:21]
	v_pk_fma_f32 v[16:17], v[16:17], v[56:57], v[22:23]
	flat_store_dwordx4 v[88:89], v[16:19] offset:528
	v_sub_f32_e32 v21, v75, v142
	v_sub_f32_e32 v20, v74, v142
	v_sub_f32_e32 v17, v69, v142
	v_sub_f32_e32 v16, v68, v142
	v_sub_f32_e32 v19, v71, v142
	v_sub_f32_e32 v18, v70, v142
	v_pk_mul_f32 v[18:19], v[142:143], v[18:19] op_sel:[1,0]
	v_pk_mul_f32 v[16:17], v[142:143], v[16:17] op_sel:[1,0]
	v_pk_fma_f32 v[18:19], v[18:19], v[34:35], v[38:39]
	v_pk_fma_f32 v[16:17], v[16:17], v[32:33], v[36:37]
	v_sub_f32_e32 v23, v77, v142
	v_sub_f32_e32 v22, v76, v142
	v_pk_mul_f32 v[22:23], v[142:143], v[22:23] op_sel:[1,0]
	v_pk_mul_f32 v[20:21], v[142:143], v[20:21] op_sel:[1,0]
	v_pk_mul_f32 v[18:19], v[18:19], s[34:35] op_sel_hi:[1,0]
	v_pk_mul_f32 v[16:17], v[16:17], s[34:35] op_sel_hi:[1,0]
	v_pk_fma_f32 v[20:21], v[20:21], v[44:45], v[48:49]
	v_pk_fma_f32 v[22:23], v[22:23], v[46:47], v[50:51]
	v_pk_fma_f32 v[12:13], v[12:13], v[52:53], v[16:17]
	v_pk_fma_f32 v[14:15], v[14:15], v[54:55], v[18:19]
	flat_store_dwordx4 v[80:81], v[12:15] offset:512
	s_nop 1
	v_pk_mul_f32 v[12:13], v[22:23], s[34:35] op_sel_hi:[1,0]
	v_pk_mul_f32 v[14:15], v[20:21], s[34:35] op_sel_hi:[1,0]
	v_pk_fma_f32 v[10:11], v[10:11], v[58:59], v[12:13]
	v_pk_fma_f32 v[8:9], v[8:9], v[56:57], v[14:15]
	flat_store_dwordx4 v[80:81], v[8:11] offset:528
	v_sub_f32_e32 v13, v91, v140
	v_sub_f32_e32 v12, v90, v140
	v_sub_f32_e32 v9, v83, v140
	v_sub_f32_e32 v8, v82, v140
	v_sub_f32_e32 v11, v85, v140
	v_sub_f32_e32 v10, v84, v140
	v_pk_mul_f32 v[10:11], v[140:141], v[10:11] op_sel:[1,0]
	v_pk_mul_f32 v[8:9], v[140:141], v[8:9] op_sel:[1,0]
	v_pk_fma_f32 v[10:11], v[10:11], v[34:35], v[38:39]
	v_pk_fma_f32 v[8:9], v[8:9], v[32:33], v[36:37]
	v_sub_f32_e32 v15, v93, v140
	v_sub_f32_e32 v14, v92, v140
	v_pk_mul_f32 v[14:15], v[140:141], v[14:15] op_sel:[1,0]
	v_pk_mul_f32 v[12:13], v[140:141], v[12:13] op_sel:[1,0]
	v_pk_mul_f32 v[10:11], v[10:11], s[34:35] op_sel_hi:[1,0]
	v_pk_mul_f32 v[8:9], v[8:9], s[34:35] op_sel_hi:[1,0]
	v_pk_fma_f32 v[12:13], v[12:13], v[44:45], v[48:49]
	v_pk_fma_f32 v[14:15], v[14:15], v[46:47], v[50:51]
	v_pk_fma_f32 v[4:5], v[4:5], v[52:53], v[8:9]
	v_pk_fma_f32 v[6:7], v[6:7], v[54:55], v[10:11]
	flat_store_dwordx4 v[72:73], v[4:7] offset:512
	s_nop 1
	v_pk_mul_f32 v[4:5], v[14:15], s[34:35] op_sel_hi:[1,0]
	v_pk_mul_f32 v[6:7], v[12:13], s[34:35] op_sel_hi:[1,0]
	v_pk_fma_f32 v[2:3], v[2:3], v[58:59], v[4:5]
	v_pk_fma_f32 v[0:1], v[0:1], v[56:57], v[6:7]
	flat_store_dwordx4 v[72:73], v[0:3] offset:528
	s_cbranch_vccnz .LBB0_1392
	s_andn2_b64 vcc, exec, s[10:11]
	s_cbranch_vccnz .LBB0_1391
	s_barrier
	s_branch .LBB0_1391
